# skinny GEMM K loops (gateA,gateB,out,up,down): per-K-step vmcnt(0) drains -> unrolled + rolling global_load prefetch with counted waits
# baseline (speedup 1.0000x reference)
; __device__ __forceinline__ f32x4 mfma16(bf16x8 a, bf16x8 b, f32x4 c) { return __builtin_amdgcn_mfma_f32_16x16x32_bf16(a, b, c, 0, 0, 0); }
; template <int RT, class Epi>
; __device__ __forceinline__ void skinny_gemm(const bf16* A, size_t lda, const bf16* Bt, int K, int N, const Epi& epi, int wg, int wg_first, int wg_count, int tid, LAS unsigned char* lds) {
;     ...
;     for (int s = me; s < nunit; s += wg_count) {
;         const int n0 = 32 * (s / NRG), r0 = (s % NRG) * (16 * RT);
;         f32x4 acc[RT][2];
; #pragma unroll
;         for (int rt = 0; rt < RT; ++rt) { acc[rt][0] = (f32x4){0.f, 0.f, 0.f, 0.f}; acc[rt][1] = (f32x4){0.f, 0.f, 0.f, 0.f}; }
;         const bf16* ap = A + (size_t)(r0 + c) * lda + (size_t)w * (K / 8) + 8 * g;
;         const bf16* bp = Bt + (size_t)(n0 + c) * K + (size_t)w * (K / 8) + 8 * g;
; #pragma unroll 4
;         for (int ks = 0; ks < ksteps; ++ks) {
;             bf16x8 af[RT], bfr[2];
; #pragma unroll
;             for (int rt = 0; rt < RT; ++rt) af[rt] = *(const bf16x8*)(ap + (size_t)(16 * rt) * lda + 32 * ks);
;             bfr[0] = *(const bf16x8*)(bp + 32 * ks); bfr[1] = *(const bf16x8*)(bp + (size_t)16 * K + 32 * ks);
; #pragma unroll
;             for (int rt = 0; rt < RT; ++rt) { acc[rt][0] = mfma16(af[rt], bfr[0], acc[rt][0]); acc[rt][1] = mfma16(af[rt], bfr[1], acc[rt][1]); }
;         }
.LBB0_987:
	s_and_b32 s16, s13, 0x70
	v_or_b32_e32 v0, s16, v26
	s_and_b32 s15, s12, 0x7fffffe0
	v_lshlrev_b32_e32 v10, 11, v0
	v_lshl_add_u64 v[40:41], v[8:9], 0, v[10:11]
	v_or_b32_e32 v10, s15, v26
	v_lshlrev_b64 v[0:1], 11, v[10:11]
	v_lshl_add_u64 v[42:43], v[12:13], 0, v[0:1]
	v_add_co_u32_e32 v44, vcc, 0x8000, v42
	v_mov_b32_e32 v132, v40
	v_mov_b32_e32 v133, v41
	s_nop 0
	v_mov_b32_e32 v168, v42
	v_mov_b32_e32 v169, v43
	s_nop 0
	v_addc_co_u32_e32 v45, vcc, 0, v43, vcc
	v_mov_b32_e32 v174, v44
	v_mov_b32_e32 v175, v45
	s_nop 0
	global_load_dwordx4 v[112:115], v[132:133], off
	global_load_dwordx4 v[128:131], v[168:169], off
	global_load_dwordx4 v[164:167], v[174:175], off
	global_load_dwordx4 v[116:119], v[132:133], off offset:64
	global_load_dwordx4 v[136:139], v[168:169], off offset:64
	global_load_dwordx4 v[188:191], v[174:175], off offset:64
	global_load_dwordx4 v[120:123], v[132:133], off offset:128
	global_load_dwordx4 v[140:143], v[168:169], off offset:128
	global_load_dwordx4 v[192:195], v[174:175], off offset:128
	global_load_dwordx4 v[124:127], v[132:133], off offset:192
	global_load_dwordx4 v[144:147], v[168:169], off offset:192
	global_load_dwordx4 v[196:199], v[174:175], off offset:192
	s_waitcnt vmcnt(9) lgkmcnt(0)
	v_mov_b32_e32 v0, v112
	v_mov_b32_e32 v1, v113
	v_mov_b32_e32 v2, v114
	v_mov_b32_e32 v3, v115
	v_mov_b32_e32 v4, v128
	v_mov_b32_e32 v5, v129
	v_mov_b32_e32 v6, v130
	v_mov_b32_e32 v7, v131
	v_mov_b32_e32 v14, v164
	v_mov_b32_e32 v15, v165
	v_mov_b32_e32 v16, v166
	v_mov_b32_e32 v17, v167
	s_nop 1
	v_mfma_f32_16x16x32_bf16 v[4:7], v[0:3], v[4:7], 0
	v_mfma_f32_16x16x32_bf16 v[0:3], v[0:3], v[14:17], 0
	s_nop 0
	s_nop 0
	s_nop 0
	s_waitcnt vmcnt(6) lgkmcnt(0)
	v_mov_b32_e32 v14, v116
	v_mov_b32_e32 v15, v117
	v_mov_b32_e32 v16, v118
	v_mov_b32_e32 v17, v119
	v_mov_b32_e32 v18, v136
	v_mov_b32_e32 v19, v137
	v_mov_b32_e32 v20, v138
	v_mov_b32_e32 v21, v139
	v_mov_b32_e32 v22, v188
	v_mov_b32_e32 v23, v189
	v_mov_b32_e32 v24, v190
	v_mov_b32_e32 v25, v191
	s_nop 1
	v_mfma_f32_16x16x32_bf16 v[4:7], v[14:17], v[18:21], v[4:7]
	v_mfma_f32_16x16x32_bf16 v[0:3], v[14:17], v[22:25], v[0:3]
	s_nop 0
	s_nop 0
	s_nop 0
	s_waitcnt vmcnt(3) lgkmcnt(0)
	v_mov_b32_e32 v14, v120
	v_mov_b32_e32 v15, v121
	v_mov_b32_e32 v16, v122
	v_mov_b32_e32 v17, v123
	v_mov_b32_e32 v18, v140
	v_mov_b32_e32 v19, v141
	v_mov_b32_e32 v20, v142
	v_mov_b32_e32 v21, v143
	v_mov_b32_e32 v22, v192
	v_mov_b32_e32 v23, v193
	v_mov_b32_e32 v24, v194
	v_mov_b32_e32 v25, v195
	s_nop 1
	v_mfma_f32_16x16x32_bf16 v[4:7], v[14:17], v[18:21], v[4:7]
	v_mfma_f32_16x16x32_bf16 v[0:3], v[14:17], v[22:25], v[0:3]
	s_nop 0
	s_nop 0
	s_nop 0
	s_waitcnt vmcnt(0) lgkmcnt(0)
	v_mov_b32_e32 v14, v124
	v_mov_b32_e32 v15, v125
	v_mov_b32_e32 v16, v126
	v_mov_b32_e32 v17, v127
	v_mov_b32_e32 v18, v144
	v_mov_b32_e32 v19, v145
	v_mov_b32_e32 v20, v146
	v_mov_b32_e32 v21, v147
	v_mov_b32_e32 v22, v196
	v_mov_b32_e32 v23, v197
	v_mov_b32_e32 v24, v198
	v_mov_b32_e32 v25, v199
	s_nop 1
	v_mfma_f32_16x16x32_bf16 v[4:7], v[14:17], v[18:21], v[4:7]
	v_mfma_f32_16x16x32_bf16 v[0:3], v[14:17], v[22:25], v[0:3]
	s_nop 7
	ds_write2_b32 v38, v4, v0 offset1:16
	ds_write2_b32 v38, v5, v1 offset0:32 offset1:48
	ds_write2_b32 v38, v6, v2 offset0:64 offset1:80
	ds_write2_b32 v38, v7, v3 offset0:96 offset1:112
	s_waitcnt lgkmcnt(0)
	s_barrier
	s_and_saveexec_b64 s[2:3], s[6:7]
	s_cbranch_execz .LBB0_986
; #define LAS __attribute__((address_space(3)))
; __device__ __forceinline__ void sync_threads() { __syncthreads(); }
; template <int RT, class Epi>
; __device__ __forceinline__ void skinny_gemm(const bf16* A, size_t lda, const bf16* Bt, int K, int N, const Epi& epi, int wg, int wg_first, int wg_count, int tid, LAS unsigned char* lds) {
;     ...
;         if (RT == 8 || tid < 64 * RT) {
;             const int row = tid >> 2, c8 = (tid & 3) * 8;
;             f32x4 v0 = (f32x4){0.f, 0.f, 0.f, 0.f}, v1 = (f32x4){0.f, 0.f, 0.f, 0.f};
; #pragma unroll
;             for (int ww = 0; ww < 8; ++ww) { const LAS float* pp = (const LAS float*)(lds + ww * SK_PART) + row * 32 + c8; v0 = v0 + *(const LAS f32x4*)pp; v1 = v1 + *(const LAS f32x4*)(pp + 4); }
;             epi(r0 + row, n0 + c8, v0, v1);
;         }
;         sync_threads();
	ds_read_b128 v[0:3], v29
	ds_read_b128 v[4:7], v29 offset:16
	v_add_u32_e32 v20, s16, v27
	v_or_b32_e32 v10, s15, v28
	v_lshlrev_b32_e32 v24, 1, v10
	s_waitcnt lgkmcnt(1)
	v_pk_add_f32 v[14:15], v[2:3], 0 op_sel_hi:[1,0]
	v_pk_add_f32 v[16:17], v[0:1], 0 op_sel_hi:[1,0]
	ds_read_b128 v[0:3], v29 offset:16384
	s_waitcnt lgkmcnt(1)
	v_pk_add_f32 v[6:7], v[6:7], 0 op_sel_hi:[1,0]
	v_pk_add_f32 v[4:5], v[4:5], 0 op_sel_hi:[1,0]
	v_mov_b32_e32 v25, v11
	v_ashrrev_i32_e32 v21, 31, v20
	s_waitcnt lgkmcnt(0)
	v_pk_add_f32 v[14:15], v[14:15], v[2:3]
	v_pk_add_f32 v[16:17], v[16:17], v[0:1]
	ds_read_b128 v[0:3], v29 offset:16400
	s_waitcnt lgkmcnt(0)
	v_pk_add_f32 v[6:7], v[6:7], v[2:3]
	v_pk_add_f32 v[4:5], v[4:5], v[0:1]
	ds_read_b128 v[0:3], v29 offset:32768
	s_waitcnt lgkmcnt(0)
	v_pk_add_f32 v[14:15], v[14:15], v[2:3]
	v_pk_add_f32 v[16:17], v[16:17], v[0:1]
	ds_read_b128 v[0:3], v29 offset:32784
	s_waitcnt lgkmcnt(0)
	v_pk_add_f32 v[6:7], v[6:7], v[2:3]
	v_pk_add_f32 v[4:5], v[4:5], v[0:1]
	ds_read_b128 v[0:3], v29 offset:49152
	s_waitcnt lgkmcnt(0)
	v_pk_add_f32 v[14:15], v[14:15], v[2:3]
	v_pk_add_f32 v[16:17], v[16:17], v[0:1]
	ds_read_b128 v[0:3], v29 offset:49168
	s_waitcnt lgkmcnt(0)
	v_pk_add_f32 v[6:7], v[6:7], v[2:3]
	v_pk_add_f32 v[4:5], v[4:5], v[0:1]
	ds_read_b128 v[0:3], v30
	s_waitcnt lgkmcnt(0)
	v_pk_add_f32 v[14:15], v[14:15], v[2:3]
	v_pk_add_f32 v[16:17], v[16:17], v[0:1]
	ds_read_b128 v[0:3], v31
	s_waitcnt lgkmcnt(0)
	v_pk_add_f32 v[6:7], v[6:7], v[2:3]
	v_pk_add_f32 v[4:5], v[4:5], v[0:1]
	ds_read_b128 v[0:3], v32
	s_waitcnt lgkmcnt(0)
	v_pk_add_f32 v[14:15], v[14:15], v[2:3]
	v_pk_add_f32 v[16:17], v[16:17], v[0:1]
	ds_read_b128 v[0:3], v33
	s_waitcnt lgkmcnt(0)
	v_pk_add_f32 v[6:7], v[6:7], v[2:3]
	v_pk_add_f32 v[4:5], v[4:5], v[0:1]
	ds_read_b128 v[0:3], v34
	s_waitcnt lgkmcnt(0)
	v_pk_add_f32 v[14:15], v[14:15], v[2:3]
	v_pk_add_f32 v[18:19], v[16:17], v[0:1]
	ds_read_b128 v[0:3], v35
	s_waitcnt lgkmcnt(0)
	v_pk_add_f32 v[6:7], v[6:7], v[2:3]
	v_pk_add_f32 v[4:5], v[4:5], v[0:1]
	ds_read_b128 v[0:3], v36
	s_waitcnt lgkmcnt(0)
	v_pk_add_f32 v[16:17], v[14:15], v[2:3]
	v_pk_add_f32 v[22:23], v[18:19], v[0:1]
	ds_read_b128 v[0:3], v37
	s_waitcnt lgkmcnt(0)
	v_pk_add_f32 v[18:19], v[4:5], v[0:1]
	v_mov_b64_e32 v[0:1], s[10:11]
	v_mad_i64_i32 v[0:1], s[16:17], v20, s77, v[0:1]
	v_lshl_add_u64 v[0:1], v[0:1], 0, v[24:25]
	v_pk_add_f32 v[14:15], v[6:7], v[2:3]
	global_load_dwordx4 v[0:3], v[0:1], off
	v_lshl_add_u64 v[4:5], v[10:11], 2, s[0:1]
	s_waitcnt vmcnt(0) lgkmcnt(0)
	v_lshlrev_b32_e32 v41, 16, v0
	v_and_b32_e32 v42, 0xffff0000, v0
	v_lshlrev_b32_e32 v43, 16, v1
	v_and_b32_e32 v40, 0xffff0000, v1
	v_lshlrev_b32_e32 v44, 16, v2
	v_and_b32_e32 v45, 0xffff0000, v2
	v_lshlrev_b32_e32 v46, 16, v3
	v_and_b32_e32 v39, 0xffff0000, v3
	global_load_dwordx4 v[0:3], v[4:5], off offset:16
	s_nop 0
	global_load_dwordx4 v[4:7], v[4:5], off
	s_waitcnt vmcnt(1)
	v_add_f32_e32 v0, v0, v44
	v_add_f32_e32 v1, v1, v45
	v_add_f32_e32 v2, v2, v46
	v_mul_f32_e32 v0, 0xbfb8aa3b, v0
	v_mul_f32_e32 v1, 0xbfb8aa3b, v1
	v_mul_f32_e32 v2, 0xbfb8aa3b, v2
	v_exp_f32_e32 v0, v0
	v_exp_f32_e32 v1, v1
	v_exp_f32_e32 v2, v2
	s_waitcnt vmcnt(0)
	v_add_f32_e32 v4, v4, v41
	v_add_f32_e32 v0, 1.0, v0
	v_add_f32_e32 v1, 1.0, v1
	v_add_f32_e32 v2, 1.0, v2
	v_rcp_f32_e32 v0, v0
	v_rcp_f32_e32 v1, v1
	v_rcp_f32_e32 v2, v2
	v_mul_f32_e32 v4, 0xbfb8aa3b, v4
	v_mul_f32_e32 v10, v18, v0
	v_add_f32_e32 v0, v5, v42
	v_mul_f32_e32 v5, v19, v1
	v_add_f32_e32 v1, v6, v43
	v_mul_f32_e32 v6, v14, v2
	v_add_f32_e32 v2, v7, v40
	v_mul_f32_e32 v0, 0xbfb8aa3b, v0
	v_mul_f32_e32 v1, 0xbfb8aa3b, v1
	v_mul_f32_e32 v2, 0xbfb8aa3b, v2
	v_exp_f32_e32 v4, v4
	v_exp_f32_e32 v0, v0
	v_exp_f32_e32 v1, v1
	v_exp_f32_e32 v2, v2
	v_add_f32_e32 v3, v3, v39
	v_mul_f32_e32 v3, 0xbfb8aa3b, v3
	v_exp_f32_e32 v3, v3
	v_add_f32_e32 v4, 1.0, v4
	v_add_f32_e32 v0, 1.0, v0
	v_add_f32_e32 v1, 1.0, v1
	v_add_f32_e32 v2, 1.0, v2
	v_rcp_f32_e32 v4, v4
	v_rcp_f32_e32 v0, v0
	v_rcp_f32_e32 v1, v1
	v_rcp_f32_e32 v2, v2
	v_add_f32_e32 v3, 1.0, v3
	v_rcp_f32_e32 v3, v3
	v_mul_f32_e32 v4, v22, v4
	v_mul_f32_e32 v0, v23, v0
	v_mul_f32_e32 v1, v16, v1
	v_mul_f32_e32 v2, v17, v2
	v_cvt_pk_bf16_f32 v0, v4, v0
	v_cvt_pk_bf16_f32 v1, v1, v2
	v_cvt_pk_bf16_f32 v2, v10, v5
	v_lshlrev_b64 v[4:5], 11, v[20:21]
	v_lshl_add_u64 v[4:5], s[8:9], 0, v[4:5]
	v_mul_f32_e32 v3, v15, v3
	v_lshl_add_u64 v[4:5], v[4:5], 0, v[24:25]
	v_cvt_pk_bf16_f32 v3, v6, v3
	global_store_dwordx4 v[4:5], v[0:3], off
	s_branch .LBB0_986

; __device__ __forceinline__ f32x4 mfma16(bf16x8 a, bf16x8 b, f32x4 c) { return __builtin_amdgcn_mfma_f32_16x16x32_bf16(a, b, c, 0, 0, 0); }
; template <int RT, class Epi>
; __device__ __forceinline__ void skinny_gemm(const bf16* A, size_t lda, const bf16* Bt, int K, int N, const Epi& epi, int wg, int wg_first, int wg_count, int tid, LAS unsigned char* lds) {
;     ...
;     for (int s = me; s < nunit; s += wg_count) {
;         const int n0 = 32 * (s / NRG), r0 = (s % NRG) * (16 * RT);
;         f32x4 acc[RT][2];
; #pragma unroll
;         for (int rt = 0; rt < RT; ++rt) { acc[rt][0] = (f32x4){0.f, 0.f, 0.f, 0.f}; acc[rt][1] = (f32x4){0.f, 0.f, 0.f, 0.f}; }
;         const bf16* ap = A + (size_t)(r0 + c) * lda + (size_t)w * (K / 8) + 8 * g;
;         const bf16* bp = Bt + (size_t)(n0 + c) * K + (size_t)w * (K / 8) + 8 * g;
; #pragma unroll 4
;         for (int ks = 0; ks < ksteps; ++ks) {
;             bf16x8 af[RT], bfr[2];
; #pragma unroll
;             for (int rt = 0; rt < RT; ++rt) af[rt] = *(const bf16x8*)(ap + (size_t)(16 * rt) * lda + 32 * ks);
;             bfr[0] = *(const bf16x8*)(bp + 32 * ks); bfr[1] = *(const bf16x8*)(bp + (size_t)16 * K + 32 * ks);
; #pragma unroll
;             for (int rt = 0; rt < RT; ++rt) { acc[rt][0] = mfma16(af[rt], bfr[0], acc[rt][0]); acc[rt][1] = mfma16(af[rt], bfr[1], acc[rt][1]); }
;         }
.LBB0_1012:
	s_lshl_b32 s8, s15, 12
	s_and_b32 s8, s8, 0x70000
	v_lshl_or_b32 v10, v38, 1, s8
	s_and_b32 s8, s14, 0x7fffffe0
	v_lshl_add_u64 v[14:15], v[8:9], 0, v[10:11]
	v_or_b32_e32 v10, s8, v26
	v_lshlrev_b64 v[0:1], 12, v[10:11]
	v_lshl_add_u64 v[16:17], v[12:13], 0, v[0:1]
	v_mov_b32_e32 v0, 0
	s_mov_b64 s[8:9], 0
	v_mov_b32_e32 v1, v0
	v_mov_b32_e32 v2, v0
	v_mov_b32_e32 v3, v0
	v_mov_b32_e32 v4, v0
	v_mov_b32_e32 v5, v0
	v_mov_b32_e32 v6, v0
	v_mov_b32_e32 v7, v0
	v_lshl_add_u64 v[18:19], v[14:15], 0, s[8:9]
	v_add_co_u32_e32 v44, vcc, 0x36600000, v18
	v_lshl_add_u64 v[40:41], v[16:17], 0, s[8:9]
	s_nop 0
	v_addc_co_u32_e32 v45, vcc, 0, v19, vcc
	v_mov_b32_e32 v132, v44
	v_mov_b32_e32 v133, v45
	s_nop 0
	v_add_co_u32_e32 v46, vcc, 0x6a80000, v40
	s_add_u32 s8, s8, 0x100
	s_nop 0
	v_addc_co_u32_e32 v47, vcc, 0, v41, vcc
	v_add_co_u32_e32 v48, vcc, 0x6a90000, v40
	v_mov_b32_e32 v208, v46
	v_mov_b32_e32 v209, v47
	s_nop 0
	s_nop 0
	v_addc_co_u32_e32 v49, vcc, 0, v41, vcc
	v_mov_b32_e32 v210, v48
	v_mov_b32_e32 v211, v49
	s_nop 0
	s_addc_u32 s9, s9, 0
	s_cmpk_eq_i32 s8, 0x200
	global_load_dwordx4 v[112:115], v[132:133], off
	global_load_dwordx4 v[136:139], v[208:209], off
	global_load_dwordx4 v[172:175], v[210:211], off
	global_load_dwordx4 v[116:119], v[132:133], off offset:64
	global_load_dwordx4 v[140:143], v[208:209], off offset:64
	global_load_dwordx4 v[192:195], v[210:211], off offset:64
	global_load_dwordx4 v[120:123], v[132:133], off offset:128
	global_load_dwordx4 v[144:147], v[208:209], off offset:128
	global_load_dwordx4 v[196:199], v[210:211], off offset:128
	global_load_dwordx4 v[124:127], v[132:133], off offset:192
	global_load_dwordx4 v[164:167], v[208:209], off offset:192
	global_load_dwordx4 v[200:203], v[210:211], off offset:192
	global_load_dwordx4 v[128:131], v[132:133], off offset:256
	global_load_dwordx4 v[168:171], v[208:209], off offset:256
	global_load_dwordx4 v[204:207], v[210:211], off offset:256
	s_waitcnt vmcnt(12) lgkmcnt(0)
	v_mov_b32_e32 v18, v112
	v_mov_b32_e32 v19, v113
	v_mov_b32_e32 v20, v114
	v_mov_b32_e32 v21, v115
	v_mov_b32_e32 v22, v136
	v_mov_b32_e32 v23, v137
	v_mov_b32_e32 v24, v138
	v_mov_b32_e32 v25, v139
	v_mov_b32_e32 v40, v172
	v_mov_b32_e32 v41, v173
	v_mov_b32_e32 v42, v174
	v_mov_b32_e32 v43, v175
	s_nop 1
	global_load_dwordx4 v[112:115], v[132:133], off offset:320
	global_load_dwordx4 v[136:139], v[208:209], off offset:320
	global_load_dwordx4 v[172:175], v[210:211], off offset:320
	v_mfma_f32_16x16x32_bf16 v[0:3], v[18:21], v[22:25], v[0:3]
	v_mfma_f32_16x16x32_bf16 v[4:7], v[18:21], v[40:43], v[4:7]
	s_nop 0
	s_nop 0
	s_nop 0
	s_waitcnt vmcnt(12) lgkmcnt(0)
	v_mov_b32_e32 v18, v116
	v_mov_b32_e32 v19, v117
	v_mov_b32_e32 v20, v118
	v_mov_b32_e32 v21, v119
	v_mov_b32_e32 v22, v140
	v_mov_b32_e32 v23, v141
	v_mov_b32_e32 v24, v142
	v_mov_b32_e32 v25, v143
	v_mov_b32_e32 v40, v192
	v_mov_b32_e32 v41, v193
	v_mov_b32_e32 v42, v194
	v_mov_b32_e32 v43, v195
	s_nop 1
	global_load_dwordx4 v[116:119], v[132:133], off offset:384
	global_load_dwordx4 v[140:143], v[208:209], off offset:384
	global_load_dwordx4 v[192:195], v[210:211], off offset:384
	v_mfma_f32_16x16x32_bf16 v[0:3], v[18:21], v[22:25], v[0:3]
	v_mfma_f32_16x16x32_bf16 v[4:7], v[18:21], v[40:43], v[4:7]
	s_nop 0
	s_nop 0
	s_nop 0
	s_waitcnt vmcnt(12) lgkmcnt(0)
	v_mov_b32_e32 v18, v120
	v_mov_b32_e32 v19, v121
	v_mov_b32_e32 v20, v122
	v_mov_b32_e32 v21, v123
	v_mov_b32_e32 v22, v144
	v_mov_b32_e32 v23, v145
	v_mov_b32_e32 v24, v146
	v_mov_b32_e32 v25, v147
	v_mov_b32_e32 v40, v196
	v_mov_b32_e32 v41, v197
	v_mov_b32_e32 v42, v198
	v_mov_b32_e32 v43, v199
	s_nop 1
	global_load_dwordx4 v[120:123], v[132:133], off offset:448
	global_load_dwordx4 v[144:147], v[208:209], off offset:448
	global_load_dwordx4 v[196:199], v[210:211], off offset:448
	v_mfma_f32_16x16x32_bf16 v[0:3], v[18:21], v[22:25], v[0:3]
	v_mfma_f32_16x16x32_bf16 v[4:7], v[18:21], v[40:43], v[4:7]
	s_nop 0
	s_nop 0
	s_nop 0
	s_waitcnt vmcnt(12) lgkmcnt(0)
	v_mov_b32_e32 v18, v124
	v_mov_b32_e32 v19, v125
	v_mov_b32_e32 v20, v126
	v_mov_b32_e32 v21, v127
	v_mov_b32_e32 v22, v164
	v_mov_b32_e32 v23, v165
	v_mov_b32_e32 v24, v166
	v_mov_b32_e32 v25, v167
	v_mov_b32_e32 v40, v200
	v_mov_b32_e32 v41, v201
	v_mov_b32_e32 v42, v202
	v_mov_b32_e32 v43, v203
	s_nop 1
	v_mfma_f32_16x16x32_bf16 v[0:3], v[18:21], v[22:25], v[0:3]
	v_mfma_f32_16x16x32_bf16 v[4:7], v[18:21], v[40:43], v[4:7]
	s_nop 0
	v_lshl_add_u64 v[18:19], v[14:15], 0, s[8:9]
	v_add_co_u32_e32 v44, vcc, 0x36600000, v18
	v_lshl_add_u64 v[40:41], v[16:17], 0, s[8:9]
	s_nop 0
	v_addc_co_u32_e32 v45, vcc, 0, v19, vcc
	s_nop 0
	v_add_co_u32_e32 v46, vcc, 0x6a80000, v40
	s_add_u32 s8, s8, 0x100
	s_nop 0
	v_addc_co_u32_e32 v47, vcc, 0, v41, vcc
	v_add_co_u32_e32 v48, vcc, 0x6a90000, v40
	s_nop 0
	s_nop 0
	v_addc_co_u32_e32 v49, vcc, 0, v41, vcc
	s_nop 0
	s_addc_u32 s9, s9, 0
	s_cmpk_eq_i32 s8, 0x200
	s_waitcnt vmcnt(9) lgkmcnt(0)
	v_mov_b32_e32 v18, v128
	v_mov_b32_e32 v19, v129
	v_mov_b32_e32 v20, v130
	v_mov_b32_e32 v21, v131
	v_mov_b32_e32 v22, v168
	v_mov_b32_e32 v23, v169
	v_mov_b32_e32 v24, v170
	v_mov_b32_e32 v25, v171
	v_mov_b32_e32 v40, v204
	v_mov_b32_e32 v41, v205
	v_mov_b32_e32 v42, v206
	v_mov_b32_e32 v43, v207
	s_nop 1
	v_mfma_f32_16x16x32_bf16 v[0:3], v[18:21], v[22:25], v[0:3]
	v_mfma_f32_16x16x32_bf16 v[4:7], v[18:21], v[40:43], v[4:7]
	s_nop 0
	s_nop 0
	s_nop 0
	s_waitcnt vmcnt(6) lgkmcnt(0)
; #define LAS __attribute__((address_space(3)))
; __device__ __forceinline__ f32x4 mfma16(bf16x8 a, bf16x8 b, f32x4 c) { return __builtin_amdgcn_mfma_f32_16x16x32_bf16(a, b, c, 0, 0, 0); }
; __device__ __forceinline__ void sync_threads() { __syncthreads(); }
; template <int RT, class Epi>
; __device__ __forceinline__ void skinny_gemm(const bf16* A, size_t lda, const bf16* Bt, int K, int N, const Epi& epi, int wg, int wg_first, int wg_count, int tid, LAS unsigned char* lds) {
;     ...
; #pragma unroll 4
;         for (int ks = 0; ks < ksteps; ++ks) {
;             bf16x8 af[RT], bfr[2];
; #pragma unroll
;             for (int rt = 0; rt < RT; ++rt) af[rt] = *(const bf16x8*)(ap + (size_t)(16 * rt) * lda + 32 * ks);
;             bfr[0] = *(const bf16x8*)(bp + 32 * ks); bfr[1] = *(const bf16x8*)(bp + (size_t)16 * K + 32 * ks);
; #pragma unroll
;             for (int rt = 0; rt < RT; ++rt) { acc[rt][0] = mfma16(af[rt], bfr[0], acc[rt][0]); acc[rt][1] = mfma16(af[rt], bfr[1], acc[rt][1]); }
;         }
;         LAS float* part = (LAS float*)(lds + w * SK_PART);
; #pragma unroll
;         for (int rt = 0; rt < RT; ++rt)
; #pragma unroll
;             for (int nt = 0; nt < 2; ++nt)
; #pragma unroll
;                 for (int r = 0; r < 4; ++r) part[(16 * rt + 4 * g + r) * 32 + 16 * nt + c] = acc[rt][nt][r];
;         sync_threads();
;         if (RT == 8 || tid < 64 * RT) {
;             const int row = tid >> 2, c8 = (tid & 3) * 8;
;             f32x4 v0 = (f32x4){0.f, 0.f, 0.f, 0.f}, v1 = (f32x4){0.f, 0.f, 0.f, 0.f};
; #pragma unroll
;             for (int ww = 0; ww < 8; ++ww) { const LAS float* pp = (const LAS float*)(lds + ww * SK_PART) + row * 32 + c8; v0 = v0 + *(const LAS f32x4*)pp; v1 = v1 + *(const LAS f32x4*)(pp + 4); }
;             epi(r0 + row, n0 + c8, v0, v1);
;         }
;         sync_threads();
	v_mov_b32_e32 v18, v112
	v_mov_b32_e32 v19, v113
	v_mov_b32_e32 v20, v114
	v_mov_b32_e32 v21, v115
	v_mov_b32_e32 v22, v136
	v_mov_b32_e32 v23, v137
	v_mov_b32_e32 v24, v138
	v_mov_b32_e32 v25, v139
	v_mov_b32_e32 v40, v172
	v_mov_b32_e32 v41, v173
	v_mov_b32_e32 v42, v174
	v_mov_b32_e32 v43, v175
	s_nop 1
	v_mfma_f32_16x16x32_bf16 v[0:3], v[18:21], v[22:25], v[0:3]
	v_mfma_f32_16x16x32_bf16 v[4:7], v[18:21], v[40:43], v[4:7]
	s_nop 0
	s_nop 0
	s_nop 0
	s_waitcnt vmcnt(3) lgkmcnt(0)
	v_mov_b32_e32 v18, v116
	v_mov_b32_e32 v19, v117
	v_mov_b32_e32 v20, v118
	v_mov_b32_e32 v21, v119
	v_mov_b32_e32 v22, v140
	v_mov_b32_e32 v23, v141
	v_mov_b32_e32 v24, v142
	v_mov_b32_e32 v25, v143
	v_mov_b32_e32 v40, v192
	v_mov_b32_e32 v41, v193
	v_mov_b32_e32 v42, v194
	v_mov_b32_e32 v43, v195
	s_nop 1
	v_mfma_f32_16x16x32_bf16 v[0:3], v[18:21], v[22:25], v[0:3]
	v_mfma_f32_16x16x32_bf16 v[4:7], v[18:21], v[40:43], v[4:7]
	s_nop 0
	s_nop 0
	s_nop 0
	s_waitcnt vmcnt(0) lgkmcnt(0)
	v_mov_b32_e32 v18, v120
	v_mov_b32_e32 v19, v121
	v_mov_b32_e32 v20, v122
	v_mov_b32_e32 v21, v123
	v_mov_b32_e32 v22, v144
	v_mov_b32_e32 v23, v145
	v_mov_b32_e32 v24, v146
	v_mov_b32_e32 v25, v147
	v_mov_b32_e32 v40, v196
	v_mov_b32_e32 v41, v197
	v_mov_b32_e32 v42, v198
	v_mov_b32_e32 v43, v199
	s_nop 1
	v_mfma_f32_16x16x32_bf16 v[0:3], v[18:21], v[22:25], v[0:3]
	v_mfma_f32_16x16x32_bf16 v[4:7], v[18:21], v[40:43], v[4:7]
	s_nop 0
	s_nop 6
	ds_write2_b32 v39, v0, v4 offset1:16
	ds_write2_b32 v39, v1, v5 offset0:32 offset1:48
	ds_write2_b32 v39, v2, v6 offset0:64 offset1:80
	ds_write2_b32 v39, v3, v7 offset0:96 offset1:112
	s_waitcnt lgkmcnt(0)
	s_barrier
	s_and_saveexec_b64 s[8:9], s[6:7]
	s_cbranch_execz .LBB0_1011
	ds_read_b128 v[0:3], v29
	ds_read_b128 v[4:7], v29 offset:16
	s_lshl_b32 s17, s16, 2
	s_lshl_b32 s18, s16, 4
	s_and_b32 s17, s17, 0x7fffffe0
	s_waitcnt lgkmcnt(1)
	v_pk_add_f32 v[14:15], v[2:3], 0 op_sel_hi:[1,0]
	v_pk_add_f32 v[16:17], v[0:1], 0 op_sel_hi:[1,0]
	ds_read_b128 v[0:3], v29 offset:16384
	s_waitcnt lgkmcnt(1)
	v_pk_add_f32 v[6:7], v[6:7], 0 op_sel_hi:[1,0]
	v_pk_add_f32 v[4:5], v[4:5], 0 op_sel_hi:[1,0]
	s_and_b32 s18, s18, 0x70
	v_add_u32_e32 v24, s18, v27
	s_waitcnt lgkmcnt(0)
	v_pk_add_f32 v[14:15], v[14:15], v[2:3]
	v_pk_add_f32 v[16:17], v[16:17], v[0:1]
	ds_read_b128 v[0:3], v29 offset:16400
	v_or_b32_e32 v10, s17, v28
	v_lshlrev_b32_e32 v22, 1, v10
	v_mov_b32_e32 v23, v11
	v_ashrrev_i32_e32 v25, 31, v24
	s_waitcnt lgkmcnt(0)
	v_pk_add_f32 v[6:7], v[6:7], v[2:3]
	v_pk_add_f32 v[4:5], v[4:5], v[0:1]
	ds_read_b128 v[0:3], v29 offset:32768
	s_waitcnt lgkmcnt(0)
	v_pk_add_f32 v[14:15], v[14:15], v[2:3]
	v_pk_add_f32 v[16:17], v[16:17], v[0:1]
	ds_read_b128 v[0:3], v29 offset:32784
	s_waitcnt lgkmcnt(0)
	v_pk_add_f32 v[6:7], v[6:7], v[2:3]
	v_pk_add_f32 v[4:5], v[4:5], v[0:1]
	ds_read_b128 v[0:3], v29 offset:49152
	s_waitcnt lgkmcnt(0)
	v_pk_add_f32 v[14:15], v[14:15], v[2:3]
	v_pk_add_f32 v[16:17], v[16:17], v[0:1]
	ds_read_b128 v[0:3], v29 offset:49168
	s_waitcnt lgkmcnt(0)
	v_pk_add_f32 v[6:7], v[6:7], v[2:3]
	v_pk_add_f32 v[4:5], v[4:5], v[0:1]
	ds_read_b128 v[0:3], v30
	s_waitcnt lgkmcnt(0)
	v_pk_add_f32 v[14:15], v[14:15], v[2:3]
	v_pk_add_f32 v[16:17], v[16:17], v[0:1]
	ds_read_b128 v[0:3], v31
	s_waitcnt lgkmcnt(0)
	v_pk_add_f32 v[6:7], v[6:7], v[2:3]
	v_pk_add_f32 v[4:5], v[4:5], v[0:1]
	ds_read_b128 v[0:3], v32
	s_waitcnt lgkmcnt(0)
	v_pk_add_f32 v[14:15], v[14:15], v[2:3]
	v_pk_add_f32 v[16:17], v[16:17], v[0:1]
	ds_read_b128 v[0:3], v33
	s_waitcnt lgkmcnt(0)
	v_pk_add_f32 v[6:7], v[6:7], v[2:3]
	v_pk_add_f32 v[4:5], v[4:5], v[0:1]
	ds_read_b128 v[0:3], v34
	s_waitcnt lgkmcnt(0)
	v_pk_add_f32 v[14:15], v[14:15], v[2:3]
	v_pk_add_f32 v[18:19], v[16:17], v[0:1]
	ds_read_b128 v[0:3], v35
	s_waitcnt lgkmcnt(0)
	v_pk_add_f32 v[6:7], v[6:7], v[2:3]
	v_pk_add_f32 v[4:5], v[4:5], v[0:1]
	ds_read_b128 v[0:3], v36
	s_waitcnt lgkmcnt(0)
	v_pk_add_f32 v[16:17], v[14:15], v[2:3]
	v_pk_add_f32 v[20:21], v[18:19], v[0:1]
	ds_read_b128 v[0:3], v37
	s_waitcnt lgkmcnt(0)
	v_pk_add_f32 v[18:19], v[4:5], v[0:1]
	v_mov_b64_e32 v[0:1], s[12:13]
	v_mad_i64_i32 v[0:1], s[18:19], v24, s77, v[0:1]
	v_lshl_add_u64 v[0:1], v[0:1], 0, v[22:23]
	v_pk_add_f32 v[14:15], v[6:7], v[2:3]
	global_load_dwordx4 v[0:3], v[0:1], off
	v_lshl_add_u64 v[4:5], v[10:11], 2, s[0:1]
	v_lshlrev_b64 v[24:25], 11, v[24:25]
	v_lshl_add_u64 v[42:43], s[2:3], 0, v[24:25]
	v_lshl_add_u64 v[42:43], v[42:43], 0, v[22:23]
	s_waitcnt vmcnt(0) lgkmcnt(0)
	v_lshlrev_b32_e32 v50, 16, v0
	v_and_b32_e32 v51, 0xffff0000, v0
	v_lshlrev_b32_e32 v52, 16, v1
	v_and_b32_e32 v45, 0xffff0000, v1
	v_lshlrev_b32_e32 v53, 16, v2
	v_and_b32_e32 v54, 0xffff0000, v2
	v_lshlrev_b32_e32 v55, 16, v3
	v_and_b32_e32 v40, 0xffff0000, v3
	global_load_dwordx4 v[0:3], v[4:5], off offset:16
	s_nop 0
	global_load_dwordx4 v[4:7], v[4:5], off
	s_waitcnt vmcnt(1)
	v_add_f32_e32 v0, v0, v53
	global_load_dwordx4 v[46:49], v[42:43], off
	v_mul_f32_e32 v0, 0xbfb8aa3b, v0
	v_exp_f32_e32 v0, v0
	s_waitcnt vmcnt(0)
	v_add_f32_e32 v4, v4, v50
	v_mul_f32_e32 v4, 0xbfb8aa3b, v4
	v_exp_f32_e32 v4, v4
	v_add_f32_e32 v0, 1.0, v0
	v_rcp_f32_e32 v0, v0
	v_add_f32_e32 v4, 1.0, v4
	v_rcp_f32_e32 v4, v4
	s_waitcnt lgkmcnt(0)
	v_lshlrev_b32_e32 v44, 16, v48
	v_fmac_f32_e32 v44, v18, v0
	v_add_f32_e32 v0, v5, v51
	v_mul_f32_e32 v0, 0xbfb8aa3b, v0
	v_exp_f32_e32 v0, v0
	v_and_b32_e32 v41, 0xffff0000, v46
	v_lshlrev_b32_e32 v10, 16, v46
	v_and_b32_e32 v46, 0xffff0000, v48
	v_add_f32_e32 v0, 1.0, v0
	v_rcp_f32_e32 v0, v0
	v_lshlrev_b32_e32 v42, 16, v47
	v_and_b32_e32 v43, 0xffff0000, v47
	v_lshlrev_b32_e32 v47, 16, v49
	v_fmac_f32_e32 v41, v21, v0
	v_add_f32_e32 v0, v1, v54
	v_mul_f32_e32 v0, 0xbfb8aa3b, v0
	v_exp_f32_e32 v0, v0
	v_fmac_f32_e32 v10, v20, v4
	v_lshl_add_u64 v[4:5], s[10:11], 0, v[24:25]
	v_and_b32_e32 v48, 0xffff0000, v49
	v_add_f32_e32 v0, 1.0, v0
	v_rcp_f32_e32 v0, v0
	v_lshl_add_u64 v[4:5], v[4:5], 0, v[22:23]
	v_fmac_f32_e32 v46, v19, v0
	v_add_f32_e32 v0, v6, v52
	v_mul_f32_e32 v0, 0xbfb8aa3b, v0
	v_exp_f32_e32 v0, v0
	s_nop 0
	v_add_f32_e32 v0, 1.0, v0
	v_rcp_f32_e32 v0, v0
	s_nop 0
	v_fmac_f32_e32 v42, v16, v0
	v_add_f32_e32 v0, v2, v55
	v_mul_f32_e32 v0, 0xbfb8aa3b, v0
	v_exp_f32_e32 v0, v0
	v_cvt_pk_bf16_f32 v2, v44, v46
	s_nop 0
	v_add_f32_e32 v0, 1.0, v0
	v_rcp_f32_e32 v0, v0
	s_nop 0
	v_fmac_f32_e32 v47, v14, v0
	v_add_f32_e32 v0, v7, v45
	v_mul_f32_e32 v0, 0xbfb8aa3b, v0
	v_exp_f32_e32 v0, v0
	s_nop 0
	v_add_f32_e32 v0, 1.0, v0
	v_rcp_f32_e32 v0, v0
	s_nop 0
	v_fmac_f32_e32 v43, v17, v0
	v_add_f32_e32 v0, v3, v40
	v_mul_f32_e32 v0, 0xbfb8aa3b, v0
	v_exp_f32_e32 v0, v0
	v_cvt_pk_bf16_f32 v1, v42, v43
	s_nop 0
	v_add_f32_e32 v0, 1.0, v0
	v_rcp_f32_e32 v0, v0
	s_nop 0
	v_fmac_f32_e32 v48, v15, v0
	v_cvt_pk_bf16_f32 v0, v10, v41
	v_cvt_pk_bf16_f32 v3, v47, v48
	global_store_dwordx4 v[4:5], v[0:3], off
	s_branch .LBB0_1011

; #define LAS __attribute__((address_space(3)))
; __device__ __forceinline__ f32x4 mfma16(bf16x8 a, bf16x8 b, f32x4 c) { return __builtin_amdgcn_mfma_f32_16x16x32_bf16(a, b, c, 0, 0, 0); }
; __device__ __forceinline__ void sync_threads() { __syncthreads(); }
; template <int RT, class Epi>
; __device__ __forceinline__ void skinny_gemm(const bf16* A, size_t lda, const bf16* Bt, int K, int N, const Epi& epi, int wg, int wg_first, int wg_count, int tid, LAS unsigned char* lds) {
;     ...
;         const bf16* ap = A + (size_t)(r0 + c) * lda + (size_t)w * (K / 8) + 8 * g;
;         const bf16* bp = Bt + (size_t)(n0 + c) * K + (size_t)w * (K / 8) + 8 * g;
; #pragma unroll 4
;         for (int ks = 0; ks < ksteps; ++ks) {
;             bf16x8 af[RT], bfr[2];
; #pragma unroll
;             for (int rt = 0; rt < RT; ++rt) af[rt] = *(const bf16x8*)(ap + (size_t)(16 * rt) * lda + 32 * ks);
;             bfr[0] = *(const bf16x8*)(bp + 32 * ks); bfr[1] = *(const bf16x8*)(bp + (size_t)16 * K + 32 * ks);
; #pragma unroll
;             for (int rt = 0; rt < RT; ++rt) { acc[rt][0] = mfma16(af[rt], bfr[0], acc[rt][0]); acc[rt][1] = mfma16(af[rt], bfr[1], acc[rt][1]); }
;         }
;         LAS float* part = (LAS float*)(lds + w * SK_PART);
; #pragma unroll
;         for (int rt = 0; rt < RT; ++rt)
; #pragma unroll
;             for (int nt = 0; nt < 2; ++nt)
; #pragma unroll
;                 for (int r = 0; r < 4; ++r) part[(16 * rt + 4 * g + r) * 32 + 16 * nt + c] = acc[rt][nt][r];
;         sync_threads();
;         if (RT == 8 || tid < 64 * RT) {
;             const int row = tid >> 2, c8 = (tid & 3) * 8;
;             f32x4 v0 = (f32x4){0.f, 0.f, 0.f, 0.f}, v1 = (f32x4){0.f, 0.f, 0.f, 0.f};
; #pragma unroll
;             for (int ww = 0; ww < 8; ++ww) { const LAS float* pp = (const LAS float*)(lds + ww * SK_PART) + row * 32 + c8; v0 = v0 + *(const LAS f32x4*)pp; v1 = v1 + *(const LAS f32x4*)(pp + 4); }
;             epi(r0 + row, n0 + c8, v0, v1);
;         }
;         sync_threads();
;     }
.LBB0_1084:
	s_and_b32 s16, s9, 0x70
	v_or_b32_e32 v4, s16, v20
	s_and_b32 s15, s8, 0x7fffffe0
	v_lshlrev_b32_e32 v10, 11, v4
	v_lshl_add_u64 v[8:9], v[0:1], 0, v[10:11]
	v_or_b32_e32 v10, s15, v20
	v_lshlrev_b64 v[4:5], 11, v[10:11]
	v_lshl_add_u64 v[42:43], v[2:3], 0, v[4:5]
	v_add_co_u32_e32 v44, vcc, 0x8000, v42
	v_mov_b32_e32 v132, v8
	v_mov_b32_e32 v133, v9
	s_nop 0
	v_mov_b32_e32 v168, v42
	v_mov_b32_e32 v169, v43
	s_nop 0
	v_addc_co_u32_e32 v45, vcc, 0, v43, vcc
	v_mov_b32_e32 v174, v44
	v_mov_b32_e32 v175, v45
	s_nop 0
	global_load_dwordx4 v[112:115], v[132:133], off
	global_load_dwordx4 v[128:131], v[168:169], off
	global_load_dwordx4 v[164:167], v[174:175], off
	global_load_dwordx4 v[116:119], v[132:133], off offset:64
	global_load_dwordx4 v[136:139], v[168:169], off offset:64
	global_load_dwordx4 v[188:191], v[174:175], off offset:64
	global_load_dwordx4 v[120:123], v[132:133], off offset:128
	global_load_dwordx4 v[140:143], v[168:169], off offset:128
	global_load_dwordx4 v[192:195], v[174:175], off offset:128
	global_load_dwordx4 v[124:127], v[132:133], off offset:192
	global_load_dwordx4 v[144:147], v[168:169], off offset:192
	global_load_dwordx4 v[196:199], v[174:175], off offset:192
	s_waitcnt vmcnt(9) lgkmcnt(0)
	v_mov_b32_e32 v4, v112
	v_mov_b32_e32 v5, v113
	v_mov_b32_e32 v6, v114
	v_mov_b32_e32 v7, v115
	v_mov_b32_e32 v12, v128
	v_mov_b32_e32 v13, v129
	v_mov_b32_e32 v14, v130
	v_mov_b32_e32 v15, v131
	v_mov_b32_e32 v16, v164
	v_mov_b32_e32 v17, v165
	v_mov_b32_e32 v18, v166
	v_mov_b32_e32 v19, v167
	s_nop 1
	v_mfma_f32_16x16x32_bf16 v[12:15], v[4:7], v[12:15], 0
	v_mfma_f32_16x16x32_bf16 v[4:7], v[4:7], v[16:19], 0
	s_nop 0
	s_nop 0
	s_nop 0
	s_waitcnt vmcnt(6) lgkmcnt(0)
	v_mov_b32_e32 v16, v116
	v_mov_b32_e32 v17, v117
	v_mov_b32_e32 v18, v118
	v_mov_b32_e32 v19, v119
	v_mov_b32_e32 v34, v136
	v_mov_b32_e32 v35, v137
	v_mov_b32_e32 v36, v138
	v_mov_b32_e32 v37, v139
	v_mov_b32_e32 v38, v188
	v_mov_b32_e32 v39, v189
	v_mov_b32_e32 v40, v190
	v_mov_b32_e32 v41, v191
	s_nop 1
	v_mfma_f32_16x16x32_bf16 v[12:15], v[16:19], v[34:37], v[12:15]
	v_mfma_f32_16x16x32_bf16 v[4:7], v[16:19], v[38:41], v[4:7]
	s_nop 0
	s_nop 0
	s_nop 0
	s_waitcnt vmcnt(3) lgkmcnt(0)
	v_mov_b32_e32 v16, v120
	v_mov_b32_e32 v17, v121
	v_mov_b32_e32 v18, v122
	v_mov_b32_e32 v19, v123
	v_mov_b32_e32 v34, v140
	v_mov_b32_e32 v35, v141
	v_mov_b32_e32 v36, v142
	v_mov_b32_e32 v37, v143
	v_mov_b32_e32 v38, v192
	v_mov_b32_e32 v39, v193
	v_mov_b32_e32 v40, v194
	v_mov_b32_e32 v41, v195
	s_nop 1
	v_mfma_f32_16x16x32_bf16 v[12:15], v[16:19], v[34:37], v[12:15]
	v_mfma_f32_16x16x32_bf16 v[4:7], v[16:19], v[38:41], v[4:7]
	s_nop 0
	s_nop 0
	s_nop 0
	s_waitcnt vmcnt(0) lgkmcnt(0)
	v_mov_b32_e32 v16, v124
	v_mov_b32_e32 v17, v125
	v_mov_b32_e32 v18, v126
	v_mov_b32_e32 v19, v127
	v_mov_b32_e32 v34, v144
	v_mov_b32_e32 v35, v145
	v_mov_b32_e32 v36, v146
	v_mov_b32_e32 v37, v147
	v_mov_b32_e32 v38, v196
	v_mov_b32_e32 v39, v197
	v_mov_b32_e32 v40, v198
	v_mov_b32_e32 v41, v199
	s_nop 1
	v_mfma_f32_16x16x32_bf16 v[12:15], v[16:19], v[34:37], v[12:15]
	v_mfma_f32_16x16x32_bf16 v[4:7], v[16:19], v[38:41], v[4:7]
	s_nop 7
	ds_write2_b32 v32, v12, v4 offset1:16
	ds_write2_b32 v32, v13, v5 offset0:32 offset1:48
	ds_write2_b32 v32, v14, v6 offset0:64 offset1:80
	ds_write2_b32 v32, v15, v7 offset0:96 offset1:112
	s_waitcnt lgkmcnt(0)
	s_barrier
	s_and_saveexec_b64 s[2:3], s[6:7]
	s_cbranch_execz .LBB0_1083
	ds_read_b128 v[4:7], v23
	ds_read_b128 v[12:15], v23 offset:16
	v_or_b32_e32 v10, s15, v22
	s_mov_b32 s15, 0x18000
	s_waitcnt lgkmcnt(1)
	v_pk_add_f32 v[8:9], v[6:7], 0 op_sel_hi:[1,0]
	v_pk_add_f32 v[16:17], v[4:5], 0 op_sel_hi:[1,0]
	ds_read_b128 v[4:7], v23 offset:16384
	s_waitcnt lgkmcnt(1)
	v_pk_add_f32 v[14:15], v[14:15], 0 op_sel_hi:[1,0]
	v_pk_add_f32 v[12:13], v[12:13], 0 op_sel_hi:[1,0]
	s_waitcnt lgkmcnt(0)
	v_pk_add_f32 v[8:9], v[8:9], v[6:7]
	v_pk_add_f32 v[16:17], v[16:17], v[4:5]
	ds_read_b128 v[4:7], v23 offset:16400
	s_waitcnt lgkmcnt(0)
	v_pk_add_f32 v[14:15], v[14:15], v[6:7]
	v_pk_add_f32 v[12:13], v[12:13], v[4:5]
	ds_read_b128 v[4:7], v23 offset:32768
	s_waitcnt lgkmcnt(0)
	v_pk_add_f32 v[8:9], v[8:9], v[6:7]
	v_pk_add_f32 v[16:17], v[16:17], v[4:5]
	ds_read_b128 v[4:7], v23 offset:32784
	s_waitcnt lgkmcnt(0)
	v_pk_add_f32 v[14:15], v[14:15], v[6:7]
	v_pk_add_f32 v[12:13], v[12:13], v[4:5]
	ds_read_b128 v[4:7], v23 offset:49152
	s_waitcnt lgkmcnt(0)
	v_pk_add_f32 v[8:9], v[8:9], v[6:7]
	v_pk_add_f32 v[16:17], v[16:17], v[4:5]
	ds_read_b128 v[4:7], v23 offset:49168
	s_waitcnt lgkmcnt(0)
	v_pk_add_f32 v[14:15], v[14:15], v[6:7]
	v_pk_add_f32 v[12:13], v[12:13], v[4:5]
	ds_read_b128 v[4:7], v24
	s_waitcnt lgkmcnt(0)
	v_pk_add_f32 v[8:9], v[8:9], v[6:7]
	v_pk_add_f32 v[16:17], v[16:17], v[4:5]
	ds_read_b128 v[4:7], v25
	s_waitcnt lgkmcnt(0)
	v_pk_add_f32 v[14:15], v[14:15], v[6:7]
	v_pk_add_f32 v[12:13], v[12:13], v[4:5]
	ds_read_b128 v[4:7], v26
	s_waitcnt lgkmcnt(0)
	v_pk_add_f32 v[8:9], v[8:9], v[6:7]
	v_pk_add_f32 v[16:17], v[16:17], v[4:5]
	ds_read_b128 v[4:7], v27
	s_waitcnt lgkmcnt(0)
	v_pk_add_f32 v[14:15], v[14:15], v[6:7]
	v_pk_add_f32 v[12:13], v[12:13], v[4:5]
	ds_read_b128 v[4:7], v28
	s_waitcnt lgkmcnt(0)
	v_pk_add_f32 v[8:9], v[8:9], v[6:7]
	v_pk_add_f32 v[16:17], v[16:17], v[4:5]
	ds_read_b128 v[4:7], v29
	s_waitcnt lgkmcnt(0)
	v_pk_add_f32 v[18:19], v[14:15], v[6:7]
	v_pk_add_f32 v[12:13], v[12:13], v[4:5]
	ds_read_b128 v[4:7], v30
	s_waitcnt lgkmcnt(0)
	v_pk_add_f32 v[14:15], v[8:9], v[6:7]
	v_pk_add_f32 v[16:17], v[16:17], v[4:5]
	ds_read_b128 v[4:7], v31
	v_add_u32_e32 v8, s16, v21
	v_ashrrev_i32_e32 v9, 31, v8
	s_waitcnt lgkmcnt(0)
	v_pk_add_f32 v[4:5], v[12:13], v[4:5]
	v_mov_b64_e32 v[12:13], s[12:13]
	v_mad_i64_i32 v[12:13], s[16:17], v8, s15, v[12:13]
	v_lshlrev_b64 v[8:9], 11, v[8:9]
	v_lshl_add_u64 v[38:39], v[10:11], 2, v[12:13]
	v_lshl_add_u64 v[8:9], s[10:11], 0, v[8:9]
	v_lshlrev_b32_e32 v10, 1, v10
	v_lshl_add_u64 v[8:9], v[8:9], 0, v[10:11]
	global_load_dwordx4 v[34:37], v[8:9], off
	v_pk_add_f32 v[6:7], v[18:19], v[6:7]
	s_waitcnt vmcnt(0) lgkmcnt(0)
	v_lshlrev_b32_e32 v40, 16, v34
	v_and_b32_e32 v41, 0xffff0000, v34
	v_lshlrev_b32_e32 v42, 16, v35
	v_and_b32_e32 v43, 0xffff0000, v35
	v_lshlrev_b32_e32 v12, 16, v36
	v_and_b32_e32 v13, 0xffff0000, v36
	v_lshlrev_b32_e32 v18, 16, v37
	v_and_b32_e32 v19, 0xffff0000, v37
	global_load_dwordx4 v[34:37], v[38:39], off
	s_waitcnt vmcnt(0) lgkmcnt(0)
	v_pk_fma_f32 v[14:15], v[14:15], v[36:37], v[42:43]
	v_pk_fma_f32 v[16:17], v[16:17], v[34:35], v[40:41]
	global_load_dwordx4 v[34:37], v[38:39], off offset:16
	s_waitcnt vmcnt(0) lgkmcnt(0)
	v_pk_fma_f32 v[18:19], v[6:7], v[36:37], v[18:19]
	v_pk_fma_f32 v[6:7], v[4:5], v[34:35], v[12:13]
	v_cvt_pk_bf16_f32 v4, v16, v17
	v_cvt_pk_bf16_f32 v5, v14, v15
	s_nop 0
	v_cvt_pk_bf16_f32 v6, v6, v7
	v_cvt_pk_bf16_f32 v7, v18, v19
	global_store_dwordx4 v[8:9], v[4:7], off
	s_branch .LBB0_1083

; __device__ __forceinline__ f32x4 mfma16(bf16x8 a, bf16x8 b, f32x4 c) { return __builtin_amdgcn_mfma_f32_16x16x32_bf16(a, b, c, 0, 0, 0); }
; template <int RT, class Epi>
; __device__ __forceinline__ void skinny_gemm(const bf16* A, size_t lda, const bf16* Bt, int K, int N, const Epi& epi, int wg, int wg_first, int wg_count, int tid, LAS unsigned char* lds) {
;     ...
;         const bf16* ap = A + (size_t)(r0 + c) * lda + (size_t)w * (K / 8) + 8 * g;
;         const bf16* bp = Bt + (size_t)(n0 + c) * K + (size_t)w * (K / 8) + 8 * g;
; #pragma unroll 4
;         for (int ks = 0; ks < ksteps; ++ks) {
;             bf16x8 af[RT], bfr[2];
; #pragma unroll
;             for (int rt = 0; rt < RT; ++rt) af[rt] = *(const bf16x8*)(ap + (size_t)(16 * rt) * lda + 32 * ks);
;             bfr[0] = *(const bf16x8*)(bp + 32 * ks); bfr[1] = *(const bf16x8*)(bp + (size_t)16 * K + 32 * ks);
; #pragma unroll
;             for (int rt = 0; rt < RT; ++rt) { acc[rt][0] = mfma16(af[rt], bfr[0], acc[rt][0]); acc[rt][1] = mfma16(af[rt], bfr[1], acc[rt][1]); }
;         }
.LBB0_1204:
	s_and_b32 s14, s9, 64
	v_or_b32_e32 v4, s14, v18
	v_lshlrev_b32_e32 v10, 11, v4
	v_lshl_add_u64 v[6:7], v[0:1], 0, v[10:11]
	v_add_co_u32_e32 v8, vcc, 0x8000, v6
	s_mov_b32 s2, 0x10000
	s_nop 0
	v_addc_co_u32_e32 v9, vcc, 0, v7, vcc
	s_and_b32 s13, s8, 0x7fffffe0
	v_add_co_u32_e32 v12, vcc, s2, v6
	v_or_b32_e32 v10, s13, v18
	s_nop 0
	v_addc_co_u32_e32 v13, vcc, 0, v7, vcc
	s_mov_b32 s2, 0x18000
	v_lshlrev_b64 v[4:5], 11, v[10:11]
	v_mov_b32_e32 v140, v6
	v_mov_b32_e32 v141, v7
	s_nop 0
	v_mov_b32_e32 v220, v8
	v_mov_b32_e32 v221, v9
	s_nop 0
	v_mov_b32_e32 v222, v12
	v_mov_b32_e32 v223, v13
	s_nop 0
	v_add_co_u32_e32 v14, vcc, s2, v6
	v_lshl_add_u64 v[4:5], v[2:3], 0, v[4:5]
	s_nop 0
	v_addc_co_u32_e32 v15, vcc, 0, v7, vcc
	s_mov_b32 s2, 0x8000
	v_add_co_u32_e32 v16, vcc, s2, v4
	v_mov_b32_e32 v224, v14
	v_mov_b32_e32 v225, v15
	s_nop 0
	v_mov_b32_e32 v226, v4
	v_mov_b32_e32 v227, v5
	s_nop 0
	v_addc_co_u32_e32 v17, vcc, 0, v5, vcc
	v_mov_b32_e32 v228, v16
	v_mov_b32_e32 v229, v17
	s_nop 0
	global_load_dwordx4 v[112:115], v[140:141], off
	global_load_dwordx4 v[124:127], v[220:221], off
	global_load_dwordx4 v[160:163], v[222:223], off
	global_load_dwordx4 v[172:175], v[224:225], off
	global_load_dwordx4 v[196:199], v[226:227], off
	global_load_dwordx4 v[208:211], v[228:229], off
	global_load_dwordx4 v[116:119], v[140:141], off offset:64
	global_load_dwordx4 v[128:131], v[220:221], off offset:64
	global_load_dwordx4 v[164:167], v[222:223], off offset:64
	global_load_dwordx4 v[188:191], v[224:225], off offset:64
	global_load_dwordx4 v[200:203], v[226:227], off offset:64
	global_load_dwordx4 v[212:215], v[228:229], off offset:64
	global_load_dwordx4 v[120:123], v[140:141], off offset:128
	global_load_dwordx4 v[156:159], v[220:221], off offset:128
	global_load_dwordx4 v[168:171], v[222:223], off offset:128
	global_load_dwordx4 v[192:195], v[224:225], off offset:128
	global_load_dwordx4 v[204:207], v[226:227], off offset:128
	global_load_dwordx4 v[216:219], v[228:229], off offset:128
	s_waitcnt vmcnt(12) lgkmcnt(0)
	v_mov_b32_e32 v32, v112
	v_mov_b32_e32 v33, v113
	v_mov_b32_e32 v34, v114
	v_mov_b32_e32 v35, v115
	v_mov_b32_e32 v36, v124
	v_mov_b32_e32 v37, v125
	v_mov_b32_e32 v38, v126
	v_mov_b32_e32 v39, v127
	v_mov_b32_e32 v40, v160
	v_mov_b32_e32 v41, v161
	v_mov_b32_e32 v42, v162
	v_mov_b32_e32 v43, v163
	v_mov_b32_e32 v44, v172
	v_mov_b32_e32 v45, v173
	v_mov_b32_e32 v46, v174
	v_mov_b32_e32 v47, v175
	v_mov_b32_e32 v48, v196
	v_mov_b32_e32 v49, v197
	v_mov_b32_e32 v50, v198
	v_mov_b32_e32 v51, v199
	v_mov_b32_e32 v52, v208
	v_mov_b32_e32 v53, v209
	v_mov_b32_e32 v54, v210
	v_mov_b32_e32 v55, v211
	s_nop 1
	global_load_dwordx4 v[112:115], v[140:141], off offset:192
	global_load_dwordx4 v[124:127], v[220:221], off offset:192
	global_load_dwordx4 v[160:163], v[222:223], off offset:192
	global_load_dwordx4 v[172:175], v[224:225], off offset:192
	global_load_dwordx4 v[196:199], v[226:227], off offset:192
	global_load_dwordx4 v[208:211], v[228:229], off offset:192
	v_mfma_f32_16x16x32_bf16 v[56:59], v[32:35], v[48:51], 0
	v_mfma_f32_16x16x32_bf16 v[32:35], v[32:35], v[52:55], 0
	v_mfma_f32_16x16x32_bf16 v[60:63], v[36:39], v[48:51], 0
	v_mfma_f32_16x16x32_bf16 v[36:39], v[36:39], v[52:55], 0
	v_mfma_f32_16x16x32_bf16 v[64:67], v[40:43], v[48:51], 0
	v_mfma_f32_16x16x32_bf16 v[40:43], v[40:43], v[52:55], 0
	v_mfma_f32_16x16x32_bf16 v[48:51], v[44:47], v[48:51], 0
	v_mfma_f32_16x16x32_bf16 v[44:47], v[44:47], v[52:55], 0
	s_nop 0
	s_nop 0
	s_nop 0
	s_nop 0
	s_nop 0
	s_nop 0
	s_waitcnt vmcnt(12) lgkmcnt(0)
	v_mov_b32_e32 v52, v116
	v_mov_b32_e32 v53, v117
	v_mov_b32_e32 v54, v118
	v_mov_b32_e32 v55, v119
	v_mov_b32_e32 v68, v128
	v_mov_b32_e32 v69, v129
	v_mov_b32_e32 v70, v130
	v_mov_b32_e32 v71, v131
	v_mov_b32_e32 v72, v164
	v_mov_b32_e32 v73, v165
	v_mov_b32_e32 v74, v166
	v_mov_b32_e32 v75, v167
	v_mov_b32_e32 v76, v188
	v_mov_b32_e32 v77, v189
	v_mov_b32_e32 v78, v190
	v_mov_b32_e32 v79, v191
	v_mov_b32_e32 v80, v200
	v_mov_b32_e32 v81, v201
	v_mov_b32_e32 v82, v202
	v_mov_b32_e32 v83, v203
	v_mov_b32_e32 v84, v212
	v_mov_b32_e32 v85, v213
	v_mov_b32_e32 v86, v214
	v_mov_b32_e32 v87, v215
	s_nop 1
	v_mfma_f32_16x16x32_bf16 v[56:59], v[52:55], v[80:83], v[56:59]
	v_mfma_f32_16x16x32_bf16 v[32:35], v[52:55], v[84:87], v[32:35]
	v_mfma_f32_16x16x32_bf16 v[52:55], v[68:71], v[80:83], v[60:63]
	v_mfma_f32_16x16x32_bf16 v[36:39], v[68:71], v[84:87], v[36:39]
	v_mfma_f32_16x16x32_bf16 v[60:63], v[72:75], v[80:83], v[64:67]
	v_mfma_f32_16x16x32_bf16 v[40:43], v[72:75], v[84:87], v[40:43]
	v_mfma_f32_16x16x32_bf16 v[48:51], v[76:79], v[80:83], v[48:51]
	v_mfma_f32_16x16x32_bf16 v[44:47], v[76:79], v[84:87], v[44:47]
	s_nop 0
	s_nop 0
	s_nop 0
	s_nop 0
	s_nop 0
	s_nop 0
	s_waitcnt vmcnt(6) lgkmcnt(0)
	v_mov_b32_e32 v64, v120
	v_mov_b32_e32 v65, v121
	v_mov_b32_e32 v66, v122
	v_mov_b32_e32 v67, v123
	v_mov_b32_e32 v68, v156
	v_mov_b32_e32 v69, v157
	v_mov_b32_e32 v70, v158
	v_mov_b32_e32 v71, v159
	v_mov_b32_e32 v72, v168
	v_mov_b32_e32 v73, v169
	v_mov_b32_e32 v74, v170
	v_mov_b32_e32 v75, v171
	v_mov_b32_e32 v76, v192
	v_mov_b32_e32 v77, v193
	v_mov_b32_e32 v78, v194
	v_mov_b32_e32 v79, v195
	v_mov_b32_e32 v80, v204
	v_mov_b32_e32 v81, v205
	v_mov_b32_e32 v82, v206
	v_mov_b32_e32 v83, v207
	v_mov_b32_e32 v84, v216
	v_mov_b32_e32 v85, v217
	v_mov_b32_e32 v86, v218
	v_mov_b32_e32 v87, v219
	s_nop 1
	v_mfma_f32_16x16x32_bf16 v[56:59], v[64:67], v[80:83], v[56:59]
	v_mfma_f32_16x16x32_bf16 v[32:35], v[64:67], v[84:87], v[32:35]
	v_mfma_f32_16x16x32_bf16 v[52:55], v[68:71], v[80:83], v[52:55]
	v_mfma_f32_16x16x32_bf16 v[36:39], v[68:71], v[84:87], v[36:39]
	v_mfma_f32_16x16x32_bf16 v[60:63], v[72:75], v[80:83], v[60:63]
	v_mfma_f32_16x16x32_bf16 v[40:43], v[72:75], v[84:87], v[40:43]
	v_mfma_f32_16x16x32_bf16 v[48:51], v[76:79], v[80:83], v[48:51]
	v_mfma_f32_16x16x32_bf16 v[44:47], v[76:79], v[84:87], v[44:47]
	s_nop 0
	s_nop 0
	s_nop 0
	s_nop 0
	s_nop 0
	s_nop 0
	s_nop 0
	s_nop 0
	s_nop 0
	s_nop 0
	s_waitcnt vmcnt(0) lgkmcnt(0)
; #define LAS __attribute__((address_space(3)))
; __device__ __forceinline__ f32x4 mfma16(bf16x8 a, bf16x8 b, f32x4 c) { return __builtin_amdgcn_mfma_f32_16x16x32_bf16(a, b, c, 0, 0, 0); }
; __device__ __forceinline__ void sync_threads() { __syncthreads(); }
; template <int RT, class Epi>
; __device__ __forceinline__ void skinny_gemm(const bf16* A, size_t lda, const bf16* Bt, int K, int N, const Epi& epi, int wg, int wg_first, int wg_count, int tid, LAS unsigned char* lds) {
;     ...
;             for (int rt = 0; rt < RT; ++rt) { acc[rt][0] = mfma16(af[rt], bfr[0], acc[rt][0]); acc[rt][1] = mfma16(af[rt], bfr[1], acc[rt][1]); }
;         }
;         LAS float* part = (LAS float*)(lds + w * SK_PART);
; #pragma unroll
;         for (int rt = 0; rt < RT; ++rt)
; #pragma unroll
;             for (int nt = 0; nt < 2; ++nt)
; #pragma unroll
;                 for (int r = 0; r < 4; ++r) part[(16 * rt + 4 * g + r) * 32 + 16 * nt + c] = acc[rt][nt][r];
;         sync_threads();
;         if (RT == 8 || tid < 64 * RT) {
;             const int row = tid >> 2, c8 = (tid & 3) * 8;
;             f32x4 v0 = (f32x4){0.f, 0.f, 0.f, 0.f}, v1 = (f32x4){0.f, 0.f, 0.f, 0.f};
; #pragma unroll
;             for (int ww = 0; ww < 8; ++ww) { const LAS float* pp = (const LAS float*)(lds + ww * SK_PART) + row * 32 + c8; v0 = v0 + *(const LAS f32x4*)pp; v1 = v1 + *(const LAS f32x4*)(pp + 4); }
;             epi(r0 + row, n0 + c8, v0, v1);
;         }
;         sync_threads();
	v_mov_b32_e32 v64, v112
	v_mov_b32_e32 v65, v113
	v_mov_b32_e32 v66, v114
	v_mov_b32_e32 v67, v115
	v_mov_b32_e32 v6, v124
	v_mov_b32_e32 v7, v125
	v_mov_b32_e32 v8, v126
	v_mov_b32_e32 v9, v127
	v_mov_b32_e32 v68, v160
	v_mov_b32_e32 v69, v161
	v_mov_b32_e32 v70, v162
	v_mov_b32_e32 v71, v163
	v_mov_b32_e32 v12, v172
	v_mov_b32_e32 v13, v173
	v_mov_b32_e32 v14, v174
	v_mov_b32_e32 v15, v175
	v_mov_b32_e32 v72, v196
	v_mov_b32_e32 v73, v197
	v_mov_b32_e32 v74, v198
	v_mov_b32_e32 v75, v199
	v_mov_b32_e32 v76, v208
	v_mov_b32_e32 v77, v209
	v_mov_b32_e32 v78, v210
	v_mov_b32_e32 v79, v211
	s_nop 1
	v_mfma_f32_16x16x32_bf16 v[56:59], v[64:67], v[72:75], v[56:59]
	v_mfma_f32_16x16x32_bf16 v[32:35], v[64:67], v[76:79], v[32:35]
	s_nop 7
	ds_write2_b32 v30, v56, v32 offset1:16
	ds_write2_b32 v30, v57, v33 offset0:32 offset1:48
	ds_write2_b32 v30, v58, v34 offset0:64 offset1:80
	ds_write2_b32 v30, v59, v35 offset0:96 offset1:112
	v_mfma_f32_16x16x32_bf16 v[52:55], v[6:9], v[72:75], v[52:55]
	v_mfma_f32_16x16x32_bf16 v[4:7], v[6:9], v[76:79], v[36:39]
	v_add_u32_e32 v8, 0x800, v30
	s_nop 6
	ds_write2_b32 v8, v52, v4 offset1:16
	ds_write2_b32 v8, v53, v5 offset0:32 offset1:48
	ds_write2_b32 v8, v54, v6 offset0:64 offset1:80
	ds_write2_b32 v8, v55, v7 offset0:96 offset1:112
	v_mfma_f32_16x16x32_bf16 v[36:39], v[68:71], v[72:75], v[60:63]
	v_add_u32_e32 v4, 0x1000, v30
	v_mfma_f32_16x16x32_bf16 v[40:43], v[68:71], v[76:79], v[40:43]
	s_nop 7
	ds_write2_b32 v4, v36, v40 offset1:16
	ds_write2_b32 v4, v37, v41 offset0:32 offset1:48
	ds_write2_b32 v4, v38, v42 offset0:64 offset1:80
	ds_write2_b32 v4, v39, v43 offset0:96 offset1:112
	v_mfma_f32_16x16x32_bf16 v[48:51], v[12:15], v[72:75], v[48:51]
	v_add_u32_e32 v4, 0x1800, v30
	v_mfma_f32_16x16x32_bf16 v[12:15], v[12:15], v[76:79], v[44:47]
	s_nop 7
	ds_write2_b32 v4, v48, v12 offset1:16
	ds_write2_b32 v4, v49, v13 offset0:32 offset1:48
	ds_write2_b32 v4, v50, v14 offset0:64 offset1:80
	ds_write2_b32 v4, v51, v15 offset0:96 offset1:112
	s_waitcnt lgkmcnt(0)
	s_barrier
	s_and_saveexec_b64 s[2:3], s[6:7]
	s_cbranch_execz .LBB0_1203
	ds_read_b128 v[4:7], v21
	ds_read_b128 v[12:15], v21 offset:16
	v_or_b32_e32 v10, s13, v20
	v_lshlrev_b32_e32 v10, 1, v10
	s_waitcnt lgkmcnt(1)
	v_pk_add_f32 v[8:9], v[6:7], 0 op_sel_hi:[1,0]
	v_pk_add_f32 v[16:17], v[4:5], 0 op_sel_hi:[1,0]
	ds_read_b128 v[4:7], v21 offset:16384
	s_waitcnt lgkmcnt(1)
	v_pk_add_f32 v[14:15], v[14:15], 0 op_sel_hi:[1,0]
	v_pk_add_f32 v[12:13], v[12:13], 0 op_sel_hi:[1,0]
	s_waitcnt lgkmcnt(0)
	v_pk_add_f32 v[8:9], v[8:9], v[6:7]
	v_pk_add_f32 v[16:17], v[16:17], v[4:5]
	ds_read_b128 v[4:7], v21 offset:16400
	s_waitcnt lgkmcnt(0)
	v_pk_add_f32 v[14:15], v[14:15], v[6:7]
	v_pk_add_f32 v[12:13], v[12:13], v[4:5]
	ds_read_b128 v[4:7], v21 offset:32768
	s_waitcnt lgkmcnt(0)
	v_pk_add_f32 v[8:9], v[8:9], v[6:7]
	v_pk_add_f32 v[16:17], v[16:17], v[4:5]
	ds_read_b128 v[4:7], v21 offset:32784
	s_waitcnt lgkmcnt(0)
	v_pk_add_f32 v[14:15], v[14:15], v[6:7]
	v_pk_add_f32 v[12:13], v[12:13], v[4:5]
	ds_read_b128 v[4:7], v21 offset:49152
	s_waitcnt lgkmcnt(0)
	v_pk_add_f32 v[8:9], v[8:9], v[6:7]
	v_pk_add_f32 v[16:17], v[16:17], v[4:5]
	ds_read_b128 v[4:7], v21 offset:49168
	s_waitcnt lgkmcnt(0)
	v_pk_add_f32 v[14:15], v[14:15], v[6:7]
	v_pk_add_f32 v[12:13], v[12:13], v[4:5]
	ds_read_b128 v[4:7], v22
	s_waitcnt lgkmcnt(0)
	v_pk_add_f32 v[8:9], v[8:9], v[6:7]
	v_pk_add_f32 v[16:17], v[16:17], v[4:5]
	ds_read_b128 v[4:7], v23
	s_waitcnt lgkmcnt(0)
	v_pk_add_f32 v[14:15], v[14:15], v[6:7]
	v_pk_add_f32 v[12:13], v[12:13], v[4:5]
	ds_read_b128 v[4:7], v24
	s_waitcnt lgkmcnt(0)
	v_pk_add_f32 v[8:9], v[8:9], v[6:7]
	v_pk_add_f32 v[16:17], v[16:17], v[4:5]
	ds_read_b128 v[4:7], v25
	s_waitcnt lgkmcnt(0)
	v_pk_add_f32 v[14:15], v[14:15], v[6:7]
	v_pk_add_f32 v[12:13], v[12:13], v[4:5]
	ds_read_b128 v[4:7], v26
	s_waitcnt lgkmcnt(0)
	v_pk_add_f32 v[8:9], v[8:9], v[6:7]
	v_pk_add_f32 v[16:17], v[16:17], v[4:5]
	ds_read_b128 v[4:7], v27
	s_waitcnt lgkmcnt(0)
	v_pk_add_f32 v[14:15], v[14:15], v[6:7]
	v_pk_add_f32 v[12:13], v[12:13], v[4:5]
	ds_read_b128 v[4:7], v28
	s_waitcnt lgkmcnt(0)
	v_pk_add_f32 v[8:9], v[8:9], v[6:7]
	v_pk_add_f32 v[16:17], v[16:17], v[4:5]
	ds_read_b128 v[4:7], v29
	s_waitcnt lgkmcnt(0)
	v_pk_add_f32 v[4:5], v[12:13], v[4:5]
	s_nop 0
	v_max_f32_e32 v4, 0, v4
	v_pk_add_f32 v[6:7], v[14:15], v[6:7]
	v_max_f32_e32 v13, 0, v16
	v_mul_f32_e32 v14, v4, v4
	v_max_f32_e32 v4, 0, v17
	v_add_u32_e32 v12, s14, v19
	v_mul_f32_e32 v13, v13, v13
	v_max_f32_e32 v5, 0, v5
	v_mul_f32_e32 v4, v4, v4
	v_max_f32_e32 v6, 0, v6
	v_max_f32_e32 v7, 0, v7
	v_mul_f32_e32 v15, v5, v5
	v_max_f32_e32 v5, 0, v8
	v_mul_f32_e32 v8, v6, v6
	v_mul_f32_e32 v7, v7, v7
	v_cvt_pk_bf16_f32 v4, v13, v4
	v_ashrrev_i32_e32 v13, 31, v12
	v_max_f32_e32 v6, 0, v9
	v_cvt_pk_bf16_f32 v7, v8, v7
	v_lshlrev_b64 v[8:9], 13, v[12:13]
	v_lshl_add_u64 v[8:9], s[10:11], 0, v[8:9]
	v_mul_f32_e32 v5, v5, v5
	v_mul_f32_e32 v6, v6, v6
	v_lshl_add_u64 v[8:9], v[8:9], 0, v[10:11]
	v_cvt_pk_bf16_f32 v5, v5, v6
	v_cvt_pk_bf16_f32 v6, v14, v15
	global_store_dwordx4 v[8:9], v[4:7], off
	s_branch .LBB0_1203

; __device__ __forceinline__ f32x4 mfma16(bf16x8 a, bf16x8 b, f32x4 c) { return __builtin_amdgcn_mfma_f32_16x16x32_bf16(a, b, c, 0, 0, 0); }
; template <int RT, class Epi>
; __device__ __forceinline__ void skinny_gemm(const bf16* A, size_t lda, const bf16* Bt, int K, int N, const Epi& epi, int wg, int wg_first, int wg_count, int tid, LAS unsigned char* lds) {
;     ...
;         const bf16* ap = A + (size_t)(r0 + c) * lda + (size_t)w * (K / 8) + 8 * g;
;         const bf16* bp = Bt + (size_t)(n0 + c) * K + (size_t)w * (K / 8) + 8 * g;
; #pragma unroll 4
;         for (int ks = 0; ks < ksteps; ++ks) {
;             bf16x8 af[RT], bfr[2];
; #pragma unroll
;             for (int rt = 0; rt < RT; ++rt) af[rt] = *(const bf16x8*)(ap + (size_t)(16 * rt) * lda + 32 * ks);
;             bfr[0] = *(const bf16x8*)(bp + 32 * ks); bfr[1] = *(const bf16x8*)(bp + (size_t)16 * K + 32 * ks);
; #pragma unroll
;             for (int rt = 0; rt < RT; ++rt) { acc[rt][0] = mfma16(af[rt], bfr[0], acc[rt][0]); acc[rt][1] = mfma16(af[rt], bfr[1], acc[rt][1]); }
;         }
.LBB0_1274:
	s_lshl_b32 s2, s9, 13
	s_and_b32 s2, s2, 0xe0000
	v_lshl_or_b32 v10, v32, 1, s2
	s_and_b32 s2, s8, 0x7fffffe0
	v_lshl_add_u64 v[14:15], v[8:9], 0, v[10:11]
	v_or_b32_e32 v10, s2, v20
	v_lshlrev_b64 v[0:1], 13, v[10:11]
	v_lshl_add_u64 v[16:17], v[12:13], 0, v[0:1]
	v_mov_b32_e32 v0, 0
	s_mov_b64 s[2:3], 0
	v_mov_b32_e32 v1, v0
	v_mov_b32_e32 v2, v0
	v_mov_b32_e32 v3, v0
	v_mov_b32_e32 v4, v0
	v_mov_b32_e32 v5, v0
	v_mov_b32_e32 v6, v0
	v_mov_b32_e32 v7, v0
	v_lshl_add_u64 v[18:19], v[14:15], 0, s[2:3]
	v_add_co_u32_e32 v18, vcc, 0x44900000, v18
	v_lshl_add_u64 v[42:43], v[16:17], 0, s[2:3]
	s_nop 0
	v_addc_co_u32_e32 v19, vcc, 0, v19, vcc
	v_mov_b32_e32 v132, v18
	v_mov_b32_e32 v133, v19
	s_nop 0
	v_add_co_u32_e32 v46, vcc, 0x7880000, v42
	s_add_u32 s2, s2, 0x100
	s_nop 0
	v_addc_co_u32_e32 v47, vcc, 0, v43, vcc
	v_add_co_u32_e32 v48, vcc, 0x78a0000, v42
	v_mov_b32_e32 v168, v46
	v_mov_b32_e32 v169, v47
	s_nop 0
	s_nop 0
	v_addc_co_u32_e32 v49, vcc, 0, v43, vcc
	v_mov_b32_e32 v174, v48
	v_mov_b32_e32 v175, v49
	s_nop 0
	s_addc_u32 s3, s3, 0
	s_cmpk_eq_i32 s2, 0x400
	global_load_dwordx4 v[112:115], v[132:133], off
	global_load_dwordx4 v[136:139], v[168:169], off
	global_load_dwordx4 v[192:195], v[174:175], off
	global_load_dwordx4 v[116:119], v[132:133], off offset:64
	global_load_dwordx4 v[140:143], v[168:169], off offset:64
	global_load_dwordx4 v[196:199], v[174:175], off offset:64
	global_load_dwordx4 v[120:123], v[132:133], off offset:128
	global_load_dwordx4 v[144:147], v[168:169], off offset:128
	global_load_dwordx4 v[200:203], v[174:175], off offset:128
	global_load_dwordx4 v[124:127], v[132:133], off offset:192
	global_load_dwordx4 v[164:167], v[168:169], off offset:192
	global_load_dwordx4 v[204:207], v[174:175], off offset:192
	global_load_dwordx4 v[128:131], v[132:133], off offset:256
	global_load_dwordx4 v[188:191], v[168:169], off offset:256
	global_load_dwordx4 v[208:211], v[174:175], off offset:256
	s_waitcnt vmcnt(12) lgkmcnt(0)
	v_mov_b32_e32 v34, v112
	v_mov_b32_e32 v35, v113
	v_mov_b32_e32 v36, v114
	v_mov_b32_e32 v37, v115
	v_mov_b32_e32 v38, v136
	v_mov_b32_e32 v39, v137
	v_mov_b32_e32 v40, v138
	v_mov_b32_e32 v41, v139
	v_mov_b32_e32 v42, v192
	v_mov_b32_e32 v43, v193
	v_mov_b32_e32 v44, v194
	v_mov_b32_e32 v45, v195
	s_nop 1
	global_load_dwordx4 v[112:115], v[132:133], off offset:320
	global_load_dwordx4 v[136:139], v[168:169], off offset:320
	global_load_dwordx4 v[192:195], v[174:175], off offset:320
	v_mfma_f32_16x16x32_bf16 v[0:3], v[34:37], v[38:41], v[0:3]
	v_mfma_f32_16x16x32_bf16 v[4:7], v[34:37], v[42:45], v[4:7]
	s_nop 0
	s_nop 0
	s_nop 0
	s_waitcnt vmcnt(12) lgkmcnt(0)
	v_mov_b32_e32 v34, v116
	v_mov_b32_e32 v35, v117
	v_mov_b32_e32 v36, v118
	v_mov_b32_e32 v37, v119
	v_mov_b32_e32 v38, v140
	v_mov_b32_e32 v39, v141
	v_mov_b32_e32 v40, v142
	v_mov_b32_e32 v41, v143
	v_mov_b32_e32 v42, v196
	v_mov_b32_e32 v43, v197
	v_mov_b32_e32 v44, v198
	v_mov_b32_e32 v45, v199
	s_nop 1
	global_load_dwordx4 v[116:119], v[132:133], off offset:384
	global_load_dwordx4 v[140:143], v[168:169], off offset:384
	global_load_dwordx4 v[196:199], v[174:175], off offset:384
	v_mfma_f32_16x16x32_bf16 v[0:3], v[34:37], v[38:41], v[0:3]
	v_mfma_f32_16x16x32_bf16 v[4:7], v[34:37], v[42:45], v[4:7]
	s_nop 0
	s_nop 0
	s_nop 0
	s_waitcnt vmcnt(12) lgkmcnt(0)
	v_mov_b32_e32 v34, v120
	v_mov_b32_e32 v35, v121
	v_mov_b32_e32 v36, v122
	v_mov_b32_e32 v37, v123
	v_mov_b32_e32 v38, v144
	v_mov_b32_e32 v39, v145
	v_mov_b32_e32 v40, v146
	v_mov_b32_e32 v41, v147
	v_mov_b32_e32 v42, v200
	v_mov_b32_e32 v43, v201
	v_mov_b32_e32 v44, v202
	v_mov_b32_e32 v45, v203
	s_nop 1
	global_load_dwordx4 v[120:123], v[132:133], off offset:448
	global_load_dwordx4 v[144:147], v[168:169], off offset:448
	global_load_dwordx4 v[200:203], v[174:175], off offset:448
	v_mfma_f32_16x16x32_bf16 v[0:3], v[34:37], v[38:41], v[0:3]
	v_mfma_f32_16x16x32_bf16 v[4:7], v[34:37], v[42:45], v[4:7]
	s_nop 0
	s_nop 0
	s_nop 0
	s_waitcnt vmcnt(12) lgkmcnt(0)
	v_mov_b32_e32 v34, v124
	v_mov_b32_e32 v35, v125
	v_mov_b32_e32 v36, v126
	v_mov_b32_e32 v37, v127
	v_mov_b32_e32 v38, v164
	v_mov_b32_e32 v39, v165
	v_mov_b32_e32 v40, v166
	v_mov_b32_e32 v41, v167
	v_mov_b32_e32 v42, v204
	v_mov_b32_e32 v43, v205
	v_mov_b32_e32 v44, v206
	v_mov_b32_e32 v45, v207
	s_nop 1
	global_load_dwordx4 v[124:127], v[132:133], off offset:512
	global_load_dwordx4 v[164:167], v[168:169], off offset:512
	global_load_dwordx4 v[204:207], v[174:175], off offset:512
	v_mfma_f32_16x16x32_bf16 v[0:3], v[34:37], v[38:41], v[0:3]
	v_mfma_f32_16x16x32_bf16 v[4:7], v[34:37], v[42:45], v[4:7]
	s_nop 0
	v_lshl_add_u64 v[18:19], v[14:15], 0, s[2:3]
	v_add_co_u32_e32 v18, vcc, 0x44900000, v18
	v_lshl_add_u64 v[42:43], v[16:17], 0, s[2:3]
	s_nop 0
	v_addc_co_u32_e32 v19, vcc, 0, v19, vcc
	s_nop 0
	v_add_co_u32_e32 v46, vcc, 0x7880000, v42
	s_add_u32 s2, s2, 0x100
	s_nop 0
	v_addc_co_u32_e32 v47, vcc, 0, v43, vcc
	v_add_co_u32_e32 v48, vcc, 0x78a0000, v42
	s_nop 0
	s_nop 0
	v_addc_co_u32_e32 v49, vcc, 0, v43, vcc
	s_nop 0
	s_addc_u32 s3, s3, 0
	s_cmpk_eq_i32 s2, 0x400
	s_waitcnt vmcnt(12) lgkmcnt(0)
	v_mov_b32_e32 v34, v128
	v_mov_b32_e32 v35, v129
	v_mov_b32_e32 v36, v130
	v_mov_b32_e32 v37, v131
	v_mov_b32_e32 v38, v188
	v_mov_b32_e32 v39, v189
	v_mov_b32_e32 v40, v190
	v_mov_b32_e32 v41, v191
	v_mov_b32_e32 v42, v208
	v_mov_b32_e32 v43, v209
	v_mov_b32_e32 v44, v210
	v_mov_b32_e32 v45, v211
	s_nop 1
	global_load_dwordx4 v[128:131], v[132:133], off offset:576
	global_load_dwordx4 v[188:191], v[168:169], off offset:576
	global_load_dwordx4 v[208:211], v[174:175], off offset:576
	v_mfma_f32_16x16x32_bf16 v[0:3], v[34:37], v[38:41], v[0:3]
	v_mfma_f32_16x16x32_bf16 v[4:7], v[34:37], v[42:45], v[4:7]
	s_nop 0
	s_nop 0
	s_nop 0
	s_waitcnt vmcnt(12) lgkmcnt(0)
; __device__ __forceinline__ f32x4 mfma16(bf16x8 a, bf16x8 b, f32x4 c) { return __builtin_amdgcn_mfma_f32_16x16x32_bf16(a, b, c, 0, 0, 0); }
; template <int RT, class Epi>
; __device__ __forceinline__ void skinny_gemm(const bf16* A, size_t lda, const bf16* Bt, int K, int N, const Epi& epi, int wg, int wg_first, int wg_count, int tid, LAS unsigned char* lds) {
;     ...
; #pragma unroll 4
;         for (int ks = 0; ks < ksteps; ++ks) {
;             bf16x8 af[RT], bfr[2];
; #pragma unroll
;             for (int rt = 0; rt < RT; ++rt) af[rt] = *(const bf16x8*)(ap + (size_t)(16 * rt) * lda + 32 * ks);
;             bfr[0] = *(const bf16x8*)(bp + 32 * ks); bfr[1] = *(const bf16x8*)(bp + (size_t)16 * K + 32 * ks);
; #pragma unroll
;             for (int rt = 0; rt < RT; ++rt) { acc[rt][0] = mfma16(af[rt], bfr[0], acc[rt][0]); acc[rt][1] = mfma16(af[rt], bfr[1], acc[rt][1]); }
;         }
	v_mov_b32_e32 v34, v112
	v_mov_b32_e32 v35, v113
	v_mov_b32_e32 v36, v114
	v_mov_b32_e32 v37, v115
	v_mov_b32_e32 v38, v136
	v_mov_b32_e32 v39, v137
	v_mov_b32_e32 v40, v138
	v_mov_b32_e32 v41, v139
	v_mov_b32_e32 v42, v192
	v_mov_b32_e32 v43, v193
	v_mov_b32_e32 v44, v194
	v_mov_b32_e32 v45, v195
	s_nop 1
	global_load_dwordx4 v[112:115], v[132:133], off offset:640
	global_load_dwordx4 v[136:139], v[168:169], off offset:640
	global_load_dwordx4 v[192:195], v[174:175], off offset:640
	v_mfma_f32_16x16x32_bf16 v[0:3], v[34:37], v[38:41], v[0:3]
	v_mfma_f32_16x16x32_bf16 v[4:7], v[34:37], v[42:45], v[4:7]
	s_nop 0
	s_nop 0
	s_nop 0
	s_waitcnt vmcnt(12) lgkmcnt(0)
	v_mov_b32_e32 v34, v116
	v_mov_b32_e32 v35, v117
	v_mov_b32_e32 v36, v118
	v_mov_b32_e32 v37, v119
	v_mov_b32_e32 v38, v140
	v_mov_b32_e32 v39, v141
	v_mov_b32_e32 v40, v142
	v_mov_b32_e32 v41, v143
	v_mov_b32_e32 v42, v196
	v_mov_b32_e32 v43, v197
	v_mov_b32_e32 v44, v198
	v_mov_b32_e32 v45, v199
	s_nop 1
	global_load_dwordx4 v[116:119], v[132:133], off offset:704
	global_load_dwordx4 v[140:143], v[168:169], off offset:704
	global_load_dwordx4 v[196:199], v[174:175], off offset:704
	v_mfma_f32_16x16x32_bf16 v[0:3], v[34:37], v[38:41], v[0:3]
	v_mfma_f32_16x16x32_bf16 v[4:7], v[34:37], v[42:45], v[4:7]
	s_nop 0
	s_nop 0
	s_nop 0
	s_waitcnt vmcnt(12) lgkmcnt(0)
	v_mov_b32_e32 v34, v120
	v_mov_b32_e32 v35, v121
	v_mov_b32_e32 v36, v122
	v_mov_b32_e32 v37, v123
	v_mov_b32_e32 v38, v144
	v_mov_b32_e32 v39, v145
	v_mov_b32_e32 v40, v146
	v_mov_b32_e32 v41, v147
	v_mov_b32_e32 v42, v200
	v_mov_b32_e32 v43, v201
	v_mov_b32_e32 v44, v202
	v_mov_b32_e32 v45, v203
	s_nop 1
	global_load_dwordx4 v[120:123], v[132:133], off offset:768
	global_load_dwordx4 v[144:147], v[168:169], off offset:768
	global_load_dwordx4 v[200:203], v[174:175], off offset:768
	v_mfma_f32_16x16x32_bf16 v[0:3], v[34:37], v[38:41], v[0:3]
	v_mfma_f32_16x16x32_bf16 v[4:7], v[34:37], v[42:45], v[4:7]
	s_nop 0
	v_lshl_add_u64 v[18:19], v[14:15], 0, s[2:3]
	v_add_co_u32_e32 v18, vcc, 0x44900000, v18
	v_lshl_add_u64 v[42:43], v[16:17], 0, s[2:3]
	s_nop 0
	v_addc_co_u32_e32 v19, vcc, 0, v19, vcc
	s_nop 0
	v_add_co_u32_e32 v46, vcc, 0x7880000, v42
	s_add_u32 s2, s2, 0x100
	s_nop 0
	v_addc_co_u32_e32 v47, vcc, 0, v43, vcc
	v_add_co_u32_e32 v48, vcc, 0x78a0000, v42
	s_nop 0
	s_nop 0
	v_addc_co_u32_e32 v49, vcc, 0, v43, vcc
	s_nop 0
	s_addc_u32 s3, s3, 0
	s_cmpk_eq_i32 s2, 0x400
	s_waitcnt vmcnt(12) lgkmcnt(0)
	v_mov_b32_e32 v34, v124
	v_mov_b32_e32 v35, v125
	v_mov_b32_e32 v36, v126
	v_mov_b32_e32 v37, v127
	v_mov_b32_e32 v38, v164
	v_mov_b32_e32 v39, v165
	v_mov_b32_e32 v40, v166
	v_mov_b32_e32 v41, v167
	v_mov_b32_e32 v42, v204
	v_mov_b32_e32 v43, v205
	v_mov_b32_e32 v44, v206
	v_mov_b32_e32 v45, v207
	s_nop 1
	global_load_dwordx4 v[124:127], v[132:133], off offset:832
	global_load_dwordx4 v[164:167], v[168:169], off offset:832
	global_load_dwordx4 v[204:207], v[174:175], off offset:832
	v_mfma_f32_16x16x32_bf16 v[0:3], v[34:37], v[38:41], v[0:3]
	v_mfma_f32_16x16x32_bf16 v[4:7], v[34:37], v[42:45], v[4:7]
	s_nop 0
	s_nop 0
	s_nop 0
	s_waitcnt vmcnt(12) lgkmcnt(0)
	v_mov_b32_e32 v34, v128
	v_mov_b32_e32 v35, v129
	v_mov_b32_e32 v36, v130
	v_mov_b32_e32 v37, v131
	v_mov_b32_e32 v38, v188
	v_mov_b32_e32 v39, v189
	v_mov_b32_e32 v40, v190
	v_mov_b32_e32 v41, v191
	v_mov_b32_e32 v42, v208
	v_mov_b32_e32 v43, v209
	v_mov_b32_e32 v44, v210
	v_mov_b32_e32 v45, v211
	s_nop 1
	global_load_dwordx4 v[128:131], v[132:133], off offset:896
	global_load_dwordx4 v[188:191], v[168:169], off offset:896
	global_load_dwordx4 v[208:211], v[174:175], off offset:896
	v_mfma_f32_16x16x32_bf16 v[0:3], v[34:37], v[38:41], v[0:3]
	v_mfma_f32_16x16x32_bf16 v[4:7], v[34:37], v[42:45], v[4:7]
	s_nop 0
	s_nop 0
	s_nop 0
	s_waitcnt vmcnt(12) lgkmcnt(0)
	v_mov_b32_e32 v34, v112
	v_mov_b32_e32 v35, v113
	v_mov_b32_e32 v36, v114
	v_mov_b32_e32 v37, v115
	v_mov_b32_e32 v38, v136
	v_mov_b32_e32 v39, v137
	v_mov_b32_e32 v40, v138
	v_mov_b32_e32 v41, v139
	v_mov_b32_e32 v42, v192
	v_mov_b32_e32 v43, v193
	v_mov_b32_e32 v44, v194
	v_mov_b32_e32 v45, v195
	s_nop 1
	global_load_dwordx4 v[112:115], v[132:133], off offset:960
	global_load_dwordx4 v[136:139], v[168:169], off offset:960
	global_load_dwordx4 v[192:195], v[174:175], off offset:960
	v_mfma_f32_16x16x32_bf16 v[0:3], v[34:37], v[38:41], v[0:3]
	v_mfma_f32_16x16x32_bf16 v[4:7], v[34:37], v[42:45], v[4:7]
	s_nop 0
	s_nop 0
	s_nop 0
	s_waitcnt vmcnt(12) lgkmcnt(0)
	v_mov_b32_e32 v34, v116
	v_mov_b32_e32 v35, v117
	v_mov_b32_e32 v36, v118
	v_mov_b32_e32 v37, v119
	v_mov_b32_e32 v38, v140
	v_mov_b32_e32 v39, v141
	v_mov_b32_e32 v40, v142
	v_mov_b32_e32 v41, v143
	v_mov_b32_e32 v42, v196
	v_mov_b32_e32 v43, v197
	v_mov_b32_e32 v44, v198
	v_mov_b32_e32 v45, v199
	s_nop 1
	v_mfma_f32_16x16x32_bf16 v[0:3], v[34:37], v[38:41], v[0:3]
	v_mfma_f32_16x16x32_bf16 v[4:7], v[34:37], v[42:45], v[4:7]
	s_nop 0
	v_lshl_add_u64 v[18:19], v[14:15], 0, s[2:3]
	v_add_co_u32_e32 v18, vcc, 0x44900000, v18
	v_lshl_add_u64 v[42:43], v[16:17], 0, s[2:3]
	s_nop 0
	v_addc_co_u32_e32 v19, vcc, 0, v19, vcc
	s_nop 0
	v_add_co_u32_e32 v46, vcc, 0x7880000, v42
	s_add_u32 s2, s2, 0x100
	s_nop 0
	v_addc_co_u32_e32 v47, vcc, 0, v43, vcc
	v_add_co_u32_e32 v48, vcc, 0x78a0000, v42
	s_nop 0
	s_nop 0
	v_addc_co_u32_e32 v49, vcc, 0, v43, vcc
	s_nop 0
	s_addc_u32 s3, s3, 0
	s_cmpk_eq_i32 s2, 0x400
	s_waitcnt vmcnt(9) lgkmcnt(0)
; #define LAS __attribute__((address_space(3)))
; __device__ __forceinline__ f32x4 mfma16(bf16x8 a, bf16x8 b, f32x4 c) { return __builtin_amdgcn_mfma_f32_16x16x32_bf16(a, b, c, 0, 0, 0); }
; __device__ __forceinline__ void sync_threads() { __syncthreads(); }
; template <int RT, class Epi>
; __device__ __forceinline__ void skinny_gemm(const bf16* A, size_t lda, const bf16* Bt, int K, int N, const Epi& epi, int wg, int wg_first, int wg_count, int tid, LAS unsigned char* lds) {
;     ...
;             for (int rt = 0; rt < RT; ++rt) { acc[rt][0] = mfma16(af[rt], bfr[0], acc[rt][0]); acc[rt][1] = mfma16(af[rt], bfr[1], acc[rt][1]); }
;         }
;         LAS float* part = (LAS float*)(lds + w * SK_PART);
; #pragma unroll
;         for (int rt = 0; rt < RT; ++rt)
; #pragma unroll
;             for (int nt = 0; nt < 2; ++nt)
; #pragma unroll
;                 for (int r = 0; r < 4; ++r) part[(16 * rt + 4 * g + r) * 32 + 16 * nt + c] = acc[rt][nt][r];
;         sync_threads();
;         if (RT == 8 || tid < 64 * RT) {
;             const int row = tid >> 2, c8 = (tid & 3) * 8;
;             f32x4 v0 = (f32x4){0.f, 0.f, 0.f, 0.f}, v1 = (f32x4){0.f, 0.f, 0.f, 0.f};
; #pragma unroll
;             for (int ww = 0; ww < 8; ++ww) { const LAS float* pp = (const LAS float*)(lds + ww * SK_PART) + row * 32 + c8; v0 = v0 + *(const LAS f32x4*)pp; v1 = v1 + *(const LAS f32x4*)(pp + 4); }
;             epi(r0 + row, n0 + c8, v0, v1);
;         }
;         sync_threads();
;     }
	v_mov_b32_e32 v34, v120
	v_mov_b32_e32 v35, v121
	v_mov_b32_e32 v36, v122
	v_mov_b32_e32 v37, v123
	v_mov_b32_e32 v38, v144
	v_mov_b32_e32 v39, v145
	v_mov_b32_e32 v40, v146
	v_mov_b32_e32 v41, v147
	v_mov_b32_e32 v42, v200
	v_mov_b32_e32 v43, v201
	v_mov_b32_e32 v44, v202
	v_mov_b32_e32 v45, v203
	s_nop 1
	v_mfma_f32_16x16x32_bf16 v[0:3], v[34:37], v[38:41], v[0:3]
	v_mfma_f32_16x16x32_bf16 v[4:7], v[34:37], v[42:45], v[4:7]
	s_nop 0
	s_nop 0
	s_nop 0
	s_waitcnt vmcnt(6) lgkmcnt(0)
	v_mov_b32_e32 v34, v124
	v_mov_b32_e32 v35, v125
	v_mov_b32_e32 v36, v126
	v_mov_b32_e32 v37, v127
	v_mov_b32_e32 v38, v164
	v_mov_b32_e32 v39, v165
	v_mov_b32_e32 v40, v166
	v_mov_b32_e32 v41, v167
	v_mov_b32_e32 v42, v204
	v_mov_b32_e32 v43, v205
	v_mov_b32_e32 v44, v206
	v_mov_b32_e32 v45, v207
	s_nop 1
	v_mfma_f32_16x16x32_bf16 v[0:3], v[34:37], v[38:41], v[0:3]
	v_mfma_f32_16x16x32_bf16 v[4:7], v[34:37], v[42:45], v[4:7]
	s_nop 0
	s_nop 0
	s_nop 0
	s_waitcnt vmcnt(3) lgkmcnt(0)
	v_mov_b32_e32 v34, v128
	v_mov_b32_e32 v35, v129
	v_mov_b32_e32 v36, v130
	v_mov_b32_e32 v37, v131
	v_mov_b32_e32 v38, v188
	v_mov_b32_e32 v39, v189
	v_mov_b32_e32 v40, v190
	v_mov_b32_e32 v41, v191
	v_mov_b32_e32 v42, v208
	v_mov_b32_e32 v43, v209
	v_mov_b32_e32 v44, v210
	v_mov_b32_e32 v45, v211
	s_nop 1
	v_mfma_f32_16x16x32_bf16 v[0:3], v[34:37], v[38:41], v[0:3]
	v_mfma_f32_16x16x32_bf16 v[4:7], v[34:37], v[42:45], v[4:7]
	s_nop 0
	s_nop 0
	s_nop 0
	s_waitcnt vmcnt(0) lgkmcnt(0)
	v_mov_b32_e32 v34, v112
	v_mov_b32_e32 v35, v113
	v_mov_b32_e32 v36, v114
	v_mov_b32_e32 v37, v115
	v_mov_b32_e32 v38, v136
	v_mov_b32_e32 v39, v137
	v_mov_b32_e32 v40, v138
	v_mov_b32_e32 v41, v139
	v_mov_b32_e32 v42, v192
	v_mov_b32_e32 v43, v193
	v_mov_b32_e32 v44, v194
	v_mov_b32_e32 v45, v195
	s_nop 1
	v_mfma_f32_16x16x32_bf16 v[0:3], v[34:37], v[38:41], v[0:3]
	v_mfma_f32_16x16x32_bf16 v[4:7], v[34:37], v[42:45], v[4:7]
	s_nop 0
	s_nop 6
	ds_write2_b32 v33, v0, v4 offset1:16
	ds_write2_b32 v33, v1, v5 offset0:32 offset1:48
	ds_write2_b32 v33, v2, v6 offset0:64 offset1:80
	ds_write2_b32 v33, v3, v7 offset0:96 offset1:112
	s_waitcnt lgkmcnt(0)
	s_barrier
	s_and_saveexec_b64 s[2:3], s[0:1]
	s_cbranch_execz .LBB0_1273
	ds_read_b128 v[0:3], v23
	ds_read_b128 v[4:7], v23 offset:16
	s_lshl_b32 s12, s10, 4
	s_lshl_b32 s11, s10, 2
	s_and_b32 s12, s12, 0x70
	s_waitcnt lgkmcnt(1)
	v_pk_add_f32 v[14:15], v[2:3], 0 op_sel_hi:[1,0]
	v_pk_add_f32 v[16:17], v[0:1], 0 op_sel_hi:[1,0]
	ds_read_b128 v[0:3], v23 offset:16384
	s_waitcnt lgkmcnt(1)
	v_pk_add_f32 v[6:7], v[6:7], 0 op_sel_hi:[1,0]
	v_pk_add_f32 v[4:5], v[4:5], 0 op_sel_hi:[1,0]
	s_and_b32 s11, s11, 0x7fffffe0
	v_or_b32_e32 v10, s11, v22
	s_waitcnt lgkmcnt(0)
	v_pk_add_f32 v[14:15], v[14:15], v[2:3]
	v_pk_add_f32 v[16:17], v[16:17], v[0:1]
	ds_read_b128 v[0:3], v23 offset:16400
	s_mov_b32 s11, 0x18000
	s_waitcnt lgkmcnt(0)
	v_pk_add_f32 v[6:7], v[6:7], v[2:3]
	v_pk_add_f32 v[4:5], v[4:5], v[0:1]
	ds_read_b128 v[0:3], v23 offset:32768
	s_waitcnt lgkmcnt(0)
	v_pk_add_f32 v[14:15], v[14:15], v[2:3]
	v_pk_add_f32 v[16:17], v[16:17], v[0:1]
	ds_read_b128 v[0:3], v23 offset:32784
	s_waitcnt lgkmcnt(0)
	v_pk_add_f32 v[6:7], v[6:7], v[2:3]
	v_pk_add_f32 v[4:5], v[4:5], v[0:1]
	ds_read_b128 v[0:3], v23 offset:49152
	s_waitcnt lgkmcnt(0)
	v_pk_add_f32 v[14:15], v[14:15], v[2:3]
	v_pk_add_f32 v[16:17], v[16:17], v[0:1]
	ds_read_b128 v[0:3], v23 offset:49168
	s_waitcnt lgkmcnt(0)
	v_pk_add_f32 v[6:7], v[6:7], v[2:3]
	v_pk_add_f32 v[4:5], v[4:5], v[0:1]
	ds_read_b128 v[0:3], v24
	s_waitcnt lgkmcnt(0)
	v_pk_add_f32 v[14:15], v[14:15], v[2:3]
	v_pk_add_f32 v[16:17], v[16:17], v[0:1]
	ds_read_b128 v[0:3], v25
	s_waitcnt lgkmcnt(0)
	v_pk_add_f32 v[6:7], v[6:7], v[2:3]
	v_pk_add_f32 v[4:5], v[4:5], v[0:1]
	ds_read_b128 v[0:3], v26
	s_waitcnt lgkmcnt(0)
	v_pk_add_f32 v[14:15], v[14:15], v[2:3]
	v_pk_add_f32 v[16:17], v[16:17], v[0:1]
	ds_read_b128 v[0:3], v27
	s_waitcnt lgkmcnt(0)
	v_pk_add_f32 v[6:7], v[6:7], v[2:3]
	v_pk_add_f32 v[4:5], v[4:5], v[0:1]
	ds_read_b128 v[0:3], v28
	s_waitcnt lgkmcnt(0)
	v_pk_add_f32 v[14:15], v[14:15], v[2:3]
	v_pk_add_f32 v[16:17], v[16:17], v[0:1]
	ds_read_b128 v[0:3], v29
	s_waitcnt lgkmcnt(0)
	v_pk_add_f32 v[6:7], v[6:7], v[2:3]
	v_pk_add_f32 v[4:5], v[4:5], v[0:1]
	ds_read_b128 v[0:3], v30
	s_waitcnt lgkmcnt(0)
	v_pk_add_f32 v[14:15], v[14:15], v[2:3]
	v_pk_add_f32 v[16:17], v[16:17], v[0:1]
	ds_read_b128 v[0:3], v31
	s_waitcnt lgkmcnt(0)
	v_pk_add_f32 v[0:1], v[4:5], v[0:1]
	v_add_u32_e32 v4, s12, v21
	v_pk_add_f32 v[2:3], v[6:7], v[2:3]
	v_ashrrev_i32_e32 v5, 31, v4
	v_mov_b64_e32 v[6:7], s[6:7]
	v_mad_i64_i32 v[6:7], s[12:13], v4, s11, v[6:7]
	v_lshlrev_b64 v[4:5], 11, v[4:5]
	v_lshl_add_u64 v[38:39], v[10:11], 2, v[6:7]
	v_lshl_add_u64 v[4:5], s[4:5], 0, v[4:5]
	v_lshlrev_b32_e32 v10, 1, v10
	v_lshl_add_u64 v[4:5], v[4:5], 0, v[10:11]
	global_load_dwordx4 v[34:37], v[4:5], off
	s_waitcnt vmcnt(0) lgkmcnt(0)
	v_lshlrev_b32_e32 v40, 16, v34
	v_and_b32_e32 v41, 0xffff0000, v34
	v_lshlrev_b32_e32 v42, 16, v35
	v_and_b32_e32 v43, 0xffff0000, v35
	v_lshlrev_b32_e32 v6, 16, v36
	v_and_b32_e32 v7, 0xffff0000, v36
	v_lshlrev_b32_e32 v18, 16, v37
	v_and_b32_e32 v19, 0xffff0000, v37
	global_load_dwordx4 v[34:37], v[38:39], off
	s_waitcnt vmcnt(0) lgkmcnt(0)
	v_pk_fma_f32 v[14:15], v[14:15], v[36:37], v[42:43]
	v_pk_fma_f32 v[16:17], v[16:17], v[34:35], v[40:41]
	global_load_dwordx4 v[34:37], v[38:39], off offset:16
	s_waitcnt vmcnt(0) lgkmcnt(0)
	v_pk_fma_f32 v[18:19], v[2:3], v[36:37], v[18:19]
	v_pk_fma_f32 v[2:3], v[0:1], v[34:35], v[6:7]
	v_cvt_pk_bf16_f32 v0, v16, v17
	v_cvt_pk_bf16_f32 v1, v14, v15
	s_nop 0
	v_cvt_pk_bf16_f32 v2, v2, v3
	v_cvt_pk_bf16_f32 v3, v18, v19
	global_store_dwordx4 v[4:5], v[0:3], off
	s_branch .LBB0_1273
